# s_setprio 3 instead of 1 around the MFMA blocks (timing experiment on top of previous)
# baseline (speedup 1.0000x reference)
.LBB0_382:
	s_add_u32 s2, s38, 0xfffc0080
	s_addc_u32 s3, s39, -1
	s_add_i32 s23, 0, 0x10000
	s_cmp_eq_u32 s21, 12
	s_cselect_b32 s3, s5, s3
	s_cselect_b32 s2, s8, s2
	v_add_u32_e32 v32, s23, v147
	s_cselect_b32 s65, s11, s20
	s_cselect_b32 s64, s12, s19
	s_add_i32 s57, 0, 0x14000
	ds_read_b128 v[132:135], v32
	ds_read_b128 v[136:139], v32 offset:1024
	ds_read_b128 v[162:165], v32 offset:2048
	ds_read_b128 v[166:169], v32 offset:3072
	v_add_u32_e32 v32, s57, v147
	ds_read_b128 v[170:173], v32
	ds_read_b128 v[174:177], v32 offset:1024
	ds_read_b128 v[178:181], v32 offset:2048
	ds_read_b128 v[182:185], v32 offset:3072
	v_lshl_add_u64 v[34:35], s[38:39], 0, v[150:151]
	s_add_i32 m0, s7, 0xc000
	ds_read_b128 v[186:189], v196
	ds_read_b128 v[198:201], v196 offset:1024
	ds_read_b128 v[202:205], v196 offset:2048
	ds_read_b128 v[206:209], v196 offset:3072
	ds_read_b128 v[210:213], v196 offset:4096
	ds_read_b128 v[220:223], v196 offset:5120
	ds_read_b128 v[224:227], v196 offset:6144
	ds_read_b128 v[228:231], v196 offset:7168
	global_load_lds_dwordx4 v[34:35], off
	v_lshl_add_u64 v[34:35], s[38:39], 0, v[152:153]
	s_add_i32 m0, s7, 0xe000
	s_nop 0
	global_load_lds_dwordx4 v[34:35], off
	s_waitcnt vmcnt(8)
	s_waitcnt lgkmcnt(0)
	s_barrier
	s_setprio 3
	s_waitcnt lgkmcnt(0)
	v_mfma_f32_16x16x32_bf16 v[128:131], v[132:135], v[186:189], v[128:131]
	v_mfma_f32_16x16x32_bf16 v[124:127], v[162:165], v[186:189], v[124:127]
	v_mfma_f32_16x16x32_bf16 v[112:115], v[132:135], v[202:205], v[112:115]
	v_mfma_f32_16x16x32_bf16 v[108:111], v[162:165], v[202:205], v[108:111]
	v_mfma_f32_16x16x32_bf16 v[96:99], v[132:135], v[210:213], v[96:99]
	v_mfma_f32_16x16x32_bf16 v[92:95], v[162:165], v[210:213], v[92:95]
	v_mfma_f32_16x16x32_bf16 v[80:83], v[132:135], v[224:227], v[80:83]
	v_mfma_f32_16x16x32_bf16 v[76:79], v[162:165], v[224:227], v[76:79]
	v_mfma_f32_16x16x32_bf16 v[128:131], v[136:139], v[198:201], v[128:131]
	v_mfma_f32_16x16x32_bf16 v[124:127], v[166:169], v[198:201], v[124:127]
	v_mfma_f32_16x16x32_bf16 v[112:115], v[136:139], v[206:209], v[112:115]
	v_mfma_f32_16x16x32_bf16 v[108:111], v[166:169], v[206:209], v[108:111]
	v_mfma_f32_16x16x32_bf16 v[96:99], v[136:139], v[220:223], v[96:99]
	v_mfma_f32_16x16x32_bf16 v[92:95], v[166:169], v[220:223], v[92:95]
	v_mfma_f32_16x16x32_bf16 v[80:83], v[136:139], v[228:231], v[80:83]
	v_mfma_f32_16x16x32_bf16 v[76:79], v[166:169], v[228:231], v[76:79]
	s_setprio 0
	s_setprio 3
	v_mfma_f32_16x16x32_bf16 v[120:123], v[170:173], v[186:189], v[120:123]
	v_mfma_f32_16x16x32_bf16 v[116:119], v[178:181], v[186:189], v[116:119]
	v_mfma_f32_16x16x32_bf16 v[104:107], v[170:173], v[202:205], v[104:107]
	v_mfma_f32_16x16x32_bf16 v[100:103], v[178:181], v[202:205], v[100:103]
	v_mfma_f32_16x16x32_bf16 v[88:91], v[170:173], v[210:213], v[88:91]
	v_mfma_f32_16x16x32_bf16 v[84:87], v[178:181], v[210:213], v[84:87]
	v_mfma_f32_16x16x32_bf16 v[72:75], v[170:173], v[224:227], v[72:75]
	v_mfma_f32_16x16x32_bf16 v[68:71], v[178:181], v[224:227], v[68:71]
	v_mfma_f32_16x16x32_bf16 v[120:123], v[174:177], v[198:201], v[120:123]
	v_mfma_f32_16x16x32_bf16 v[116:119], v[182:185], v[198:201], v[116:119]
	v_mfma_f32_16x16x32_bf16 v[104:107], v[174:177], v[206:209], v[104:107]
	v_mfma_f32_16x16x32_bf16 v[100:103], v[182:185], v[206:209], v[100:103]
	v_mfma_f32_16x16x32_bf16 v[88:91], v[174:177], v[220:223], v[88:91]
	v_mfma_f32_16x16x32_bf16 v[84:87], v[182:185], v[220:223], v[84:87]
	v_mfma_f32_16x16x32_bf16 v[72:75], v[174:177], v[228:231], v[72:75]
	v_mfma_f32_16x16x32_bf16 v[68:71], v[182:185], v[228:231], v[68:71]
	s_setprio 0
	s_barrier
	s_add_i32 s23, s23, s13
	v_lshl_add_u64 v[232:233], s[64:65], 0, v[140:141]
	s_mov_b32 m0, s23
	ds_read_b128 v[186:189], v196 offset:16384
	ds_read_b128 v[198:201], v196 offset:17408
	ds_read_b128 v[202:205], v196 offset:18432
	ds_read_b128 v[206:209], v196 offset:19456
	ds_read_b128 v[210:213], v196 offset:20480
	ds_read_b128 v[220:223], v196 offset:21504
	ds_read_b128 v[224:227], v196 offset:22528
	ds_read_b128 v[228:231], v196 offset:23552
	global_load_lds_dwordx4 v[232:233], off
	s_add_i32 m0, s23, 0x2000
	s_add_u32 s66, s64, 0x40000
	v_lshl_add_u64 v[234:235], s[64:65], 0, v[142:143]
	s_addc_u32 s67, s65, 0
	s_add_i32 s23, s57, s13
	global_load_lds_dwordx4 v[234:235], off
	v_lshl_add_u64 v[34:35], s[66:67], 0, v[140:141]
	s_mov_b32 m0, s23
	v_lshl_add_u64 v[236:237], s[2:3], 0, v[140:141]
	global_load_lds_dwordx4 v[34:35], off
	v_lshl_add_u64 v[34:35], s[66:67], 0, v[142:143]
	s_add_i32 m0, s23, 0x2000
	v_lshl_add_u64 v[238:239], s[2:3], 0, v[142:143]
	global_load_lds_dwordx4 v[34:35], off
	s_mov_b32 m0, s7
	s_nop 0
	global_load_lds_dwordx4 v[236:237], off
	s_mov_b32 m0, s17
	s_nop 0
	global_load_lds_dwordx4 v[238:239], off
	s_waitcnt vmcnt(8)
	s_waitcnt lgkmcnt(0)
	s_barrier
	s_setprio 3
	s_waitcnt lgkmcnt(0)
	v_mfma_f32_16x16x32_bf16 v[64:67], v[132:135], v[186:189], v[64:67]
	v_mfma_f32_16x16x32_bf16 v[60:63], v[162:165], v[186:189], v[60:63]
	v_mfma_f32_16x16x32_bf16 v[48:51], v[132:135], v[202:205], v[48:51]
	v_mfma_f32_16x16x32_bf16 v[44:47], v[162:165], v[202:205], v[44:47]
	v_mfma_f32_16x16x32_bf16 v[28:31], v[132:135], v[210:213], v[28:31]
	v_mfma_f32_16x16x32_bf16 v[24:27], v[162:165], v[210:213], v[24:27]
	v_mfma_f32_16x16x32_bf16 v[12:15], v[132:135], v[224:227], v[12:15]
	v_mfma_f32_16x16x32_bf16 v[8:11], v[162:165], v[224:227], v[8:11]
	v_mfma_f32_16x16x32_bf16 v[64:67], v[136:139], v[198:201], v[64:67]
	v_mfma_f32_16x16x32_bf16 v[60:63], v[166:169], v[198:201], v[60:63]
	v_mfma_f32_16x16x32_bf16 v[48:51], v[136:139], v[206:209], v[48:51]
	v_mfma_f32_16x16x32_bf16 v[44:47], v[166:169], v[206:209], v[44:47]
	v_mfma_f32_16x16x32_bf16 v[28:31], v[136:139], v[220:223], v[28:31]
	v_mfma_f32_16x16x32_bf16 v[24:27], v[166:169], v[220:223], v[24:27]
	v_mfma_f32_16x16x32_bf16 v[12:15], v[136:139], v[228:231], v[12:15]
	v_mfma_f32_16x16x32_bf16 v[8:11], v[166:169], v[228:231], v[8:11]
	s_setprio 0
	s_setprio 3
	v_mfma_f32_16x16x32_bf16 v[56:59], v[170:173], v[186:189], v[56:59]
	v_mfma_f32_16x16x32_bf16 v[52:55], v[178:181], v[186:189], v[52:55]
	v_mfma_f32_16x16x32_bf16 v[40:43], v[170:173], v[202:205], v[40:43]
	v_mfma_f32_16x16x32_bf16 v[34:37], v[178:181], v[202:205], v[36:39]
	v_mfma_f32_16x16x32_bf16 v[20:23], v[170:173], v[210:213], v[20:23]
	v_mfma_f32_16x16x32_bf16 v[16:19], v[178:181], v[210:213], v[16:19]
	v_mfma_f32_16x16x32_bf16 v[4:7], v[170:173], v[224:227], v[4:7]
	v_mfma_f32_16x16x32_bf16 v[0:3], v[178:181], v[224:227], v[0:3]
	v_mfma_f32_16x16x32_bf16 v[56:59], v[174:177], v[198:201], v[56:59]
	v_mfma_f32_16x16x32_bf16 v[52:55], v[182:185], v[198:201], v[52:55]
	v_mfma_f32_16x16x32_bf16 v[40:43], v[174:177], v[206:209], v[40:43]
	v_mfma_f32_16x16x32_bf16 v[34:37], v[182:185], v[206:209], v[34:37]
	v_mfma_f32_16x16x32_bf16 v[20:23], v[174:177], v[220:223], v[20:23]
	v_mfma_f32_16x16x32_bf16 v[16:19], v[182:185], v[220:223], v[16:19]
	v_mfma_f32_16x16x32_bf16 v[4:7], v[174:177], v[228:231], v[4:7]
	v_mfma_f32_16x16x32_bf16 v[0:3], v[182:185], v[228:231], v[0:3]
	s_setprio 0
	s_barrier
	s_add_i32 s23, 0, 0x18000
	v_add_u32_e32 v32, s23, v147
	s_add_i32 s57, 0, 0x1c000
	ds_read_b128 v[132:135], v32
	ds_read_b128 v[136:139], v32 offset:1024
	ds_read_b128 v[162:165], v32 offset:2048
	ds_read_b128 v[166:169], v32 offset:3072
	v_add_u32_e32 v32, s57, v147
	ds_read_b128 v[170:173], v32
	ds_read_b128 v[174:177], v32 offset:1024
	ds_read_b128 v[178:181], v32 offset:2048
	ds_read_b128 v[182:185], v32 offset:3072
	s_add_u32 s2, s2, 0x40000
	s_addc_u32 s3, s3, 0
	s_mov_b32 m0, s72
	v_lshl_add_u64 v[38:39], s[2:3], 0, v[140:141]
	ds_read_b128 v[186:189], v196 offset:32768
	ds_read_b128 v[198:201], v196 offset:33792
	ds_read_b128 v[202:205], v196 offset:34816
	ds_read_b128 v[206:209], v196 offset:35840
	ds_read_b128 v[210:213], v196 offset:36864
	ds_read_b128 v[220:223], v196 offset:37888
	ds_read_b128 v[224:227], v196 offset:38912
	ds_read_b128 v[228:231], v196 offset:39936
	global_load_lds_dwordx4 v[38:39], off
	v_lshl_add_u64 v[38:39], s[2:3], 0, v[142:143]
	s_mov_b32 m0, s73
	s_nop 0
	global_load_lds_dwordx4 v[38:39], off
	s_waitcnt vmcnt(8)
	s_waitcnt lgkmcnt(0)
	s_barrier
	s_setprio 3
	s_waitcnt lgkmcnt(0)
	v_mfma_f32_16x16x32_bf16 v[128:131], v[132:135], v[186:189], v[128:131]
	v_mfma_f32_16x16x32_bf16 v[124:127], v[162:165], v[186:189], v[124:127]
	v_mfma_f32_16x16x32_bf16 v[112:115], v[132:135], v[202:205], v[112:115]
	v_mfma_f32_16x16x32_bf16 v[108:111], v[162:165], v[202:205], v[108:111]
	v_mfma_f32_16x16x32_bf16 v[96:99], v[132:135], v[210:213], v[96:99]
	v_mfma_f32_16x16x32_bf16 v[92:95], v[162:165], v[210:213], v[92:95]
	v_mfma_f32_16x16x32_bf16 v[80:83], v[132:135], v[224:227], v[80:83]
	v_mfma_f32_16x16x32_bf16 v[76:79], v[162:165], v[224:227], v[76:79]
	v_mfma_f32_16x16x32_bf16 v[128:131], v[136:139], v[198:201], v[128:131]
	v_mfma_f32_16x16x32_bf16 v[124:127], v[166:169], v[198:201], v[124:127]
	v_mfma_f32_16x16x32_bf16 v[112:115], v[136:139], v[206:209], v[112:115]
	v_mfma_f32_16x16x32_bf16 v[108:111], v[166:169], v[206:209], v[108:111]
	v_mfma_f32_16x16x32_bf16 v[96:99], v[136:139], v[220:223], v[96:99]
	v_mfma_f32_16x16x32_bf16 v[92:95], v[166:169], v[220:223], v[92:95]
	v_mfma_f32_16x16x32_bf16 v[80:83], v[136:139], v[228:231], v[80:83]
	v_mfma_f32_16x16x32_bf16 v[76:79], v[166:169], v[228:231], v[76:79]
	s_setprio 0
	s_setprio 3
	v_mfma_f32_16x16x32_bf16 v[120:123], v[170:173], v[186:189], v[120:123]
	v_mfma_f32_16x16x32_bf16 v[116:119], v[178:181], v[186:189], v[116:119]
	v_mfma_f32_16x16x32_bf16 v[104:107], v[170:173], v[202:205], v[104:107]
	v_mfma_f32_16x16x32_bf16 v[100:103], v[178:181], v[202:205], v[100:103]
	v_mfma_f32_16x16x32_bf16 v[88:91], v[170:173], v[210:213], v[88:91]
	v_mfma_f32_16x16x32_bf16 v[84:87], v[178:181], v[210:213], v[84:87]
	v_mfma_f32_16x16x32_bf16 v[72:75], v[170:173], v[224:227], v[72:75]
	v_mfma_f32_16x16x32_bf16 v[68:71], v[178:181], v[224:227], v[68:71]
	v_mfma_f32_16x16x32_bf16 v[120:123], v[174:177], v[198:201], v[120:123]
	v_mfma_f32_16x16x32_bf16 v[116:119], v[182:185], v[198:201], v[116:119]
	v_mfma_f32_16x16x32_bf16 v[104:107], v[174:177], v[206:209], v[104:107]
	v_mfma_f32_16x16x32_bf16 v[100:103], v[182:185], v[206:209], v[100:103]
	v_mfma_f32_16x16x32_bf16 v[88:91], v[174:177], v[220:223], v[88:91]
	v_mfma_f32_16x16x32_bf16 v[84:87], v[182:185], v[220:223], v[84:87]
	v_mfma_f32_16x16x32_bf16 v[72:75], v[174:177], v[228:231], v[72:75]
	v_mfma_f32_16x16x32_bf16 v[68:71], v[182:185], v[228:231], v[68:71]
	s_setprio 0
	s_barrier
	s_add_i32 s2, s23, s13
	v_lshl_add_u64 v[38:39], v[232:233], 0, s[24:25]
	s_mov_b32 m0, s2
	ds_read_b128 v[186:189], v196 offset:49152
	ds_read_b128 v[198:201], v196 offset:50176
	ds_read_b128 v[202:205], v196 offset:51200
	ds_read_b128 v[206:209], v196 offset:52224
	ds_read_b128 v[210:213], v196 offset:53248
	ds_read_b128 v[220:223], v196 offset:54272
	ds_read_b128 v[224:227], v196 offset:55296
	ds_read_b128 v[228:231], v196 offset:56320
	global_load_lds_dwordx4 v[38:39], off
	s_add_i32 m0, s2, 0x2000
	s_add_u32 s2, s64, 0x40080
	v_lshl_add_u64 v[38:39], v[234:235], 0, s[24:25]
	s_addc_u32 s3, s65, 0
	s_add_i32 s23, s57, s13
	global_load_lds_dwordx4 v[38:39], off
	v_lshl_add_u64 v[38:39], s[2:3], 0, v[140:141]
	s_mov_b32 m0, s23
	s_nop 0
	global_load_lds_dwordx4 v[38:39], off
	v_lshl_add_u64 v[38:39], s[2:3], 0, v[142:143]
	s_add_i32 m0, s23, 0x2000
	s_nop 0
	global_load_lds_dwordx4 v[38:39], off
	v_lshl_add_u64 v[38:39], v[236:237], 0, s[24:25]
	s_mov_b32 m0, s70
	s_nop 0
	global_load_lds_dwordx4 v[38:39], off
	v_lshl_add_u64 v[38:39], v[238:239], 0, s[24:25]
	s_mov_b32 m0, s71
	s_nop 0
	global_load_lds_dwordx4 v[38:39], off
	s_waitcnt vmcnt(8)
	s_waitcnt lgkmcnt(0)
	s_barrier
	s_setprio 3
	s_waitcnt lgkmcnt(0)
	v_mfma_f32_16x16x32_bf16 v[64:67], v[132:135], v[186:189], v[64:67]
	v_mfma_f32_16x16x32_bf16 v[60:63], v[162:165], v[186:189], v[60:63]
	v_mfma_f32_16x16x32_bf16 v[48:51], v[132:135], v[202:205], v[48:51]
	v_mfma_f32_16x16x32_bf16 v[44:47], v[162:165], v[202:205], v[44:47]
	v_mfma_f32_16x16x32_bf16 v[28:31], v[132:135], v[210:213], v[28:31]
	v_mfma_f32_16x16x32_bf16 v[24:27], v[162:165], v[210:213], v[24:27]
	v_mfma_f32_16x16x32_bf16 v[12:15], v[132:135], v[224:227], v[12:15]
	v_mfma_f32_16x16x32_bf16 v[8:11], v[162:165], v[224:227], v[8:11]
	v_mfma_f32_16x16x32_bf16 v[64:67], v[136:139], v[198:201], v[64:67]
	v_mfma_f32_16x16x32_bf16 v[60:63], v[166:169], v[198:201], v[60:63]
	v_mfma_f32_16x16x32_bf16 v[48:51], v[136:139], v[206:209], v[48:51]
	v_mfma_f32_16x16x32_bf16 v[44:47], v[166:169], v[206:209], v[44:47]
	v_mfma_f32_16x16x32_bf16 v[28:31], v[136:139], v[220:223], v[28:31]
	v_mfma_f32_16x16x32_bf16 v[24:27], v[166:169], v[220:223], v[24:27]
	v_mfma_f32_16x16x32_bf16 v[12:15], v[136:139], v[228:231], v[12:15]
	v_mfma_f32_16x16x32_bf16 v[8:11], v[166:169], v[228:231], v[8:11]
	s_setprio 0
	s_setprio 3
	v_mfma_f32_16x16x32_bf16 v[56:59], v[170:173], v[186:189], v[56:59]
	v_mfma_f32_16x16x32_bf16 v[52:55], v[178:181], v[186:189], v[52:55]
	v_mfma_f32_16x16x32_bf16 v[38:41], v[170:173], v[202:205], v[40:43]
	v_mfma_f32_16x16x32_bf16 v[34:37], v[178:181], v[202:205], v[34:37]
	v_mfma_f32_16x16x32_bf16 v[20:23], v[170:173], v[210:213], v[20:23]
	v_mfma_f32_16x16x32_bf16 v[16:19], v[178:181], v[210:213], v[16:19]
	v_mfma_f32_16x16x32_bf16 v[4:7], v[170:173], v[224:227], v[4:7]
	v_mfma_f32_16x16x32_bf16 v[0:3], v[178:181], v[224:227], v[0:3]
	v_mfma_f32_16x16x32_bf16 v[56:59], v[174:177], v[198:201], v[56:59]
	v_mfma_f32_16x16x32_bf16 v[52:55], v[182:185], v[198:201], v[52:55]
	v_mfma_f32_16x16x32_bf16 v[40:43], v[174:177], v[206:209], v[38:41]
	v_mfma_f32_16x16x32_bf16 v[36:39], v[182:185], v[206:209], v[34:37]
	v_mfma_f32_16x16x32_bf16 v[20:23], v[174:177], v[220:223], v[20:23]
	v_mfma_f32_16x16x32_bf16 v[16:19], v[182:185], v[220:223], v[16:19]
	v_mfma_f32_16x16x32_bf16 v[4:7], v[174:177], v[228:231], v[4:7]
	v_mfma_f32_16x16x32_bf16 v[0:3], v[182:185], v[228:231], v[0:3]
	s_setprio 0
	s_barrier
	s_add_i32 s21, s21, 2
	s_add_u32 s38, s38, 0x100
	s_addc_u32 s39, s39, 0
	s_add_u32 s19, s19, 0x100
	s_addc_u32 s20, s20, 0
	s_cmp_gt_u32 s21, 13
	s_cbranch_scc0 .LBB0_382
	s_and_b64 vcc, exec, s[52:53]
	s_cbranch_vccz .LBB0_385
	s_barrier

.LBB0_1424:
	s_add_u32 s2, s50, 0xfffc0080
	s_addc_u32 s3, s51, -1
	s_add_i32 s55, 0, 0x10000
	s_cmp_eq_u32 s54, 12
	s_cselect_b32 s3, s21, s3
	s_cselect_b32 s2, s23, s2
	s_cselect_b32 s53, s28, s45
	s_cselect_b32 s52, s29, s43
	s_add_i32 s58, 0, 0x14000
	v_add_u32_e32 v142, s55, v191
	v_add_u32_e32 v158, s58, v191
	ds_read_b128 v[114:117], v142
	ds_read_b128 v[122:125], v142 offset:1024
	ds_read_b128 v[130:133], v142 offset:2048
	ds_read_b128 v[142:145], v142 offset:3072
	ds_read_b128 v[146:149], v158
	ds_read_b128 v[150:153], v158 offset:1024
	ds_read_b128 v[172:175], v158 offset:2048
	ds_read_b128 v[176:179], v158 offset:3072
	v_lshl_add_u64 v[158:159], s[50:51], 0, v[32:33]
	s_add_i32 m0, s63, 0xc000
	ds_read_b128 v[180:183], v193
	ds_read_b128 v[184:187], v193 offset:1024
	ds_read_b128 v[194:197], v193 offset:2048
	ds_read_b128 v[198:201], v193 offset:3072
	ds_read_b128 v[202:205], v193 offset:4096
	ds_read_b128 v[206:209], v193 offset:5120
	ds_read_b128 v[210:213], v193 offset:6144
	ds_read_b128 v[220:223], v193 offset:7168
	global_load_lds_dwordx4 v[158:159], off
	v_lshl_add_u64 v[158:159], s[50:51], 0, v[170:171]
	s_add_i32 m0, s63, 0xe000
	s_nop 0
	global_load_lds_dwordx4 v[158:159], off
	s_waitcnt vmcnt(8)
	s_waitcnt lgkmcnt(0)
	s_barrier
	s_setprio 3
	s_waitcnt lgkmcnt(0)
	v_mfma_f32_16x16x32_bf16 v[138:141], v[114:117], v[180:183], v[138:141]
	v_mfma_f32_16x16x32_bf16 v[134:137], v[130:133], v[180:183], v[134:137]
	v_mfma_f32_16x16x32_bf16 v[110:113], v[114:117], v[194:197], v[110:113]
	v_mfma_f32_16x16x32_bf16 v[106:109], v[130:133], v[194:197], v[106:109]
	v_mfma_f32_16x16x32_bf16 v[94:97], v[114:117], v[202:205], v[94:97]
	v_mfma_f32_16x16x32_bf16 v[90:93], v[130:133], v[202:205], v[90:93]
	v_mfma_f32_16x16x32_bf16 v[78:81], v[114:117], v[210:213], v[78:81]
	v_mfma_f32_16x16x32_bf16 v[74:77], v[130:133], v[210:213], v[74:77]
	v_mfma_f32_16x16x32_bf16 v[138:141], v[122:125], v[184:187], v[138:141]
	v_mfma_f32_16x16x32_bf16 v[134:137], v[142:145], v[184:187], v[134:137]
	v_mfma_f32_16x16x32_bf16 v[110:113], v[122:125], v[198:201], v[110:113]
	v_mfma_f32_16x16x32_bf16 v[106:109], v[142:145], v[198:201], v[106:109]
	v_mfma_f32_16x16x32_bf16 v[94:97], v[122:125], v[206:209], v[94:97]
	v_mfma_f32_16x16x32_bf16 v[90:93], v[142:145], v[206:209], v[90:93]
	v_mfma_f32_16x16x32_bf16 v[78:81], v[122:125], v[220:223], v[78:81]
	v_mfma_f32_16x16x32_bf16 v[74:77], v[142:145], v[220:223], v[74:77]
	s_setprio 0
	s_setprio 3
	v_mfma_f32_16x16x32_bf16 v[126:129], v[146:149], v[180:183], v[126:129]
	v_mfma_f32_16x16x32_bf16 v[118:121], v[172:175], v[180:183], v[118:121]
	v_mfma_f32_16x16x32_bf16 v[102:105], v[146:149], v[194:197], v[102:105]
	v_mfma_f32_16x16x32_bf16 v[98:101], v[172:175], v[194:197], v[98:101]
	v_mfma_f32_16x16x32_bf16 v[86:89], v[146:149], v[202:205], v[86:89]
	v_mfma_f32_16x16x32_bf16 v[82:85], v[172:175], v[202:205], v[82:85]
	v_mfma_f32_16x16x32_bf16 v[70:73], v[146:149], v[210:213], v[70:73]
	v_mfma_f32_16x16x32_bf16 v[66:69], v[172:175], v[210:213], v[66:69]
	v_mfma_f32_16x16x32_bf16 v[126:129], v[150:153], v[184:187], v[126:129]
	v_mfma_f32_16x16x32_bf16 v[118:121], v[176:179], v[184:187], v[118:121]
	v_mfma_f32_16x16x32_bf16 v[102:105], v[150:153], v[198:201], v[102:105]
	v_mfma_f32_16x16x32_bf16 v[98:101], v[176:179], v[198:201], v[98:101]
	v_mfma_f32_16x16x32_bf16 v[86:89], v[150:153], v[206:209], v[86:89]
	v_mfma_f32_16x16x32_bf16 v[82:85], v[176:179], v[206:209], v[82:85]
	v_mfma_f32_16x16x32_bf16 v[70:73], v[150:153], v[220:223], v[70:73]
	v_mfma_f32_16x16x32_bf16 v[66:69], v[176:179], v[220:223], v[66:69]
	s_setprio 0
	s_barrier
	s_add_i32 s55, s55, s62
	v_lshl_add_u64 v[158:159], s[52:53], 0, v[166:167]
	s_mov_b32 m0, s55
	ds_read_b128 v[180:183], v193 offset:16384
	ds_read_b128 v[184:187], v193 offset:17408
	ds_read_b128 v[194:197], v193 offset:18432
	ds_read_b128 v[198:201], v193 offset:19456
	ds_read_b128 v[202:205], v193 offset:20480
	ds_read_b128 v[206:209], v193 offset:21504
	ds_read_b128 v[210:213], v193 offset:22528
	ds_read_b128 v[220:223], v193 offset:23552
	global_load_lds_dwordx4 v[158:159], off
	s_add_i32 m0, s55, 0x2000
	s_add_u32 s56, s52, 0x40000
	v_lshl_add_u64 v[160:161], s[52:53], 0, v[162:163]
	s_addc_u32 s57, s53, 0
	s_add_i32 s55, s58, s62
	global_load_lds_dwordx4 v[160:161], off
	v_lshl_add_u64 v[188:189], s[56:57], 0, v[166:167]
	s_mov_b32 m0, s55
	v_lshl_add_u64 v[224:225], s[2:3], 0, v[164:165]
	global_load_lds_dwordx4 v[188:189], off
	v_lshl_add_u64 v[188:189], s[56:57], 0, v[162:163]
	s_add_i32 m0, s55, 0x2000
	s_nop 0
	global_load_lds_dwordx4 v[188:189], off
	v_lshl_add_u64 v[188:189], s[2:3], 0, v[168:169]
	s_mov_b32 m0, s63
	s_nop 0
	global_load_lds_dwordx4 v[188:189], off
	s_mov_b32 m0, s64
	s_nop 0
	global_load_lds_dwordx4 v[224:225], off
	s_waitcnt vmcnt(8)
	s_waitcnt lgkmcnt(0)
	s_barrier
	s_setprio 3
	s_waitcnt lgkmcnt(0)
	v_mfma_f32_16x16x32_bf16 v[62:65], v[114:117], v[180:183], v[62:65]
	v_mfma_f32_16x16x32_bf16 v[58:61], v[130:133], v[180:183], v[58:61]
	v_mfma_f32_16x16x32_bf16 v[46:49], v[114:117], v[194:197], v[46:49]
	v_mfma_f32_16x16x32_bf16 v[42:45], v[130:133], v[194:197], v[42:45]
	v_mfma_f32_16x16x32_bf16 v[28:31], v[114:117], v[202:205], v[28:31]
	v_mfma_f32_16x16x32_bf16 v[24:27], v[130:133], v[202:205], v[24:27]
	v_mfma_f32_16x16x32_bf16 v[12:15], v[114:117], v[210:213], v[12:15]
	v_mfma_f32_16x16x32_bf16 v[8:11], v[130:133], v[210:213], v[8:11]
	v_mfma_f32_16x16x32_bf16 v[62:65], v[122:125], v[184:187], v[62:65]
	v_mfma_f32_16x16x32_bf16 v[58:61], v[142:145], v[184:187], v[58:61]
	v_mfma_f32_16x16x32_bf16 v[46:49], v[122:125], v[198:201], v[46:49]
	v_mfma_f32_16x16x32_bf16 v[42:45], v[142:145], v[198:201], v[42:45]
	v_mfma_f32_16x16x32_bf16 v[28:31], v[122:125], v[206:209], v[28:31]
	v_mfma_f32_16x16x32_bf16 v[24:27], v[142:145], v[206:209], v[24:27]
	v_mfma_f32_16x16x32_bf16 v[12:15], v[122:125], v[220:223], v[12:15]
	v_mfma_f32_16x16x32_bf16 v[8:11], v[142:145], v[220:223], v[8:11]
	s_setprio 0
	s_setprio 3
	v_mfma_f32_16x16x32_bf16 v[54:57], v[146:149], v[180:183], v[54:57]
	v_mfma_f32_16x16x32_bf16 v[50:53], v[172:175], v[180:183], v[50:53]
	v_mfma_f32_16x16x32_bf16 v[38:41], v[146:149], v[194:197], v[38:41]
	v_mfma_f32_16x16x32_bf16 v[34:37], v[172:175], v[194:197], v[34:37]
	v_mfma_f32_16x16x32_bf16 v[20:23], v[146:149], v[202:205], v[20:23]
	v_mfma_f32_16x16x32_bf16 v[16:19], v[172:175], v[202:205], v[16:19]
	v_mfma_f32_16x16x32_bf16 v[4:7], v[146:149], v[210:213], v[4:7]
	v_mfma_f32_16x16x32_bf16 v[0:3], v[172:175], v[210:213], v[0:3]
	v_mfma_f32_16x16x32_bf16 v[54:57], v[150:153], v[184:187], v[54:57]
	v_mfma_f32_16x16x32_bf16 v[50:53], v[176:179], v[184:187], v[50:53]
	v_mfma_f32_16x16x32_bf16 v[38:41], v[150:153], v[198:201], v[38:41]
	v_mfma_f32_16x16x32_bf16 v[34:37], v[176:179], v[198:201], v[34:37]
	v_mfma_f32_16x16x32_bf16 v[20:23], v[150:153], v[206:209], v[20:23]
	v_mfma_f32_16x16x32_bf16 v[16:19], v[176:179], v[206:209], v[16:19]
	v_mfma_f32_16x16x32_bf16 v[4:7], v[150:153], v[220:223], v[4:7]
	v_mfma_f32_16x16x32_bf16 v[0:3], v[176:179], v[220:223], v[0:3]
	s_setprio 0
	s_barrier
	s_add_i32 s55, 0, 0x18000
	s_add_i32 s56, 0, 0x1c000
	v_add_u32_e32 v142, s55, v191
	v_add_u32_e32 v176, s56, v191
	ds_read_b128 v[114:117], v142
	ds_read_b128 v[122:125], v142 offset:1024
	ds_read_b128 v[130:133], v142 offset:2048
	ds_read_b128 v[142:145], v142 offset:3072
	ds_read_b128 v[146:149], v176
	ds_read_b128 v[150:153], v176 offset:1024
	ds_read_b128 v[172:175], v176 offset:2048
	ds_read_b128 v[176:179], v176 offset:3072
	s_add_u32 s2, s2, 0x40000
	s_addc_u32 s3, s3, 0
	s_mov_b32 m0, s65
	v_lshl_add_u64 v[226:227], s[2:3], 0, v[168:169]
	ds_read_b128 v[180:183], v193 offset:32768
	ds_read_b128 v[184:187], v193 offset:33792
	ds_read_b128 v[194:197], v193 offset:34816
	ds_read_b128 v[198:201], v193 offset:35840
	ds_read_b128 v[202:205], v193 offset:36864
	ds_read_b128 v[206:209], v193 offset:37888
	ds_read_b128 v[210:213], v193 offset:38912
	ds_read_b128 v[220:223], v193 offset:39936
	global_load_lds_dwordx4 v[226:227], off
	v_lshl_add_u64 v[226:227], s[2:3], 0, v[164:165]
	s_mov_b32 m0, s66
	s_nop 0
	global_load_lds_dwordx4 v[226:227], off
	s_waitcnt vmcnt(8)
	s_waitcnt lgkmcnt(0)
	s_barrier
	s_setprio 3
	s_waitcnt lgkmcnt(0)
	v_mfma_f32_16x16x32_bf16 v[138:141], v[114:117], v[180:183], v[138:141]
	v_mfma_f32_16x16x32_bf16 v[134:137], v[130:133], v[180:183], v[134:137]
	v_mfma_f32_16x16x32_bf16 v[110:113], v[114:117], v[194:197], v[110:113]
	v_mfma_f32_16x16x32_bf16 v[106:109], v[130:133], v[194:197], v[106:109]
	v_mfma_f32_16x16x32_bf16 v[94:97], v[114:117], v[202:205], v[94:97]
	v_mfma_f32_16x16x32_bf16 v[90:93], v[130:133], v[202:205], v[90:93]
	v_mfma_f32_16x16x32_bf16 v[78:81], v[114:117], v[210:213], v[78:81]
	v_mfma_f32_16x16x32_bf16 v[74:77], v[130:133], v[210:213], v[74:77]
	v_mfma_f32_16x16x32_bf16 v[138:141], v[122:125], v[184:187], v[138:141]
	v_mfma_f32_16x16x32_bf16 v[134:137], v[142:145], v[184:187], v[134:137]
	v_mfma_f32_16x16x32_bf16 v[110:113], v[122:125], v[198:201], v[110:113]
	v_mfma_f32_16x16x32_bf16 v[106:109], v[142:145], v[198:201], v[106:109]
	v_mfma_f32_16x16x32_bf16 v[94:97], v[122:125], v[206:209], v[94:97]
	v_mfma_f32_16x16x32_bf16 v[90:93], v[142:145], v[206:209], v[90:93]
	v_mfma_f32_16x16x32_bf16 v[78:81], v[122:125], v[220:223], v[78:81]
	v_mfma_f32_16x16x32_bf16 v[74:77], v[142:145], v[220:223], v[74:77]
	s_setprio 0
	s_setprio 3
	v_mfma_f32_16x16x32_bf16 v[126:129], v[146:149], v[180:183], v[126:129]
	v_mfma_f32_16x16x32_bf16 v[118:121], v[172:175], v[180:183], v[118:121]
	v_mfma_f32_16x16x32_bf16 v[102:105], v[146:149], v[194:197], v[102:105]
	v_mfma_f32_16x16x32_bf16 v[98:101], v[172:175], v[194:197], v[98:101]
	v_mfma_f32_16x16x32_bf16 v[86:89], v[146:149], v[202:205], v[86:89]
	v_mfma_f32_16x16x32_bf16 v[82:85], v[172:175], v[202:205], v[82:85]
	v_mfma_f32_16x16x32_bf16 v[70:73], v[146:149], v[210:213], v[70:73]
	v_mfma_f32_16x16x32_bf16 v[66:69], v[172:175], v[210:213], v[66:69]
	v_mfma_f32_16x16x32_bf16 v[126:129], v[150:153], v[184:187], v[126:129]
	v_mfma_f32_16x16x32_bf16 v[118:121], v[176:179], v[184:187], v[118:121]
	v_mfma_f32_16x16x32_bf16 v[102:105], v[150:153], v[198:201], v[102:105]
	v_mfma_f32_16x16x32_bf16 v[98:101], v[176:179], v[198:201], v[98:101]
	v_mfma_f32_16x16x32_bf16 v[86:89], v[150:153], v[206:209], v[86:89]
	v_mfma_f32_16x16x32_bf16 v[82:85], v[176:179], v[206:209], v[82:85]
	v_mfma_f32_16x16x32_bf16 v[70:73], v[150:153], v[220:223], v[70:73]
	v_mfma_f32_16x16x32_bf16 v[66:69], v[176:179], v[220:223], v[66:69]
	s_setprio 0
	s_barrier
	s_add_i32 s2, s55, s62
	v_lshl_add_u64 v[158:159], v[158:159], 0, s[24:25]
	s_mov_b32 m0, s2
	ds_read_b128 v[180:183], v193 offset:49152
	ds_read_b128 v[184:187], v193 offset:50176
	ds_read_b128 v[194:197], v193 offset:51200
	ds_read_b128 v[198:201], v193 offset:52224
	ds_read_b128 v[202:205], v193 offset:53248
	ds_read_b128 v[206:209], v193 offset:54272
	ds_read_b128 v[210:213], v193 offset:55296
	ds_read_b128 v[220:223], v193 offset:56320
	global_load_lds_dwordx4 v[158:159], off
	s_add_i32 m0, s2, 0x2000
	s_add_u32 s2, s52, 0x40080
	v_lshl_add_u64 v[158:159], v[160:161], 0, s[24:25]
	s_addc_u32 s3, s53, 0
	s_add_i32 s52, s56, s62
	global_load_lds_dwordx4 v[158:159], off
	v_lshl_add_u64 v[158:159], s[2:3], 0, v[166:167]
	s_mov_b32 m0, s52
	s_nop 0
	global_load_lds_dwordx4 v[158:159], off
	v_lshl_add_u64 v[158:159], s[2:3], 0, v[162:163]
	s_add_i32 m0, s52, 0x2000
	s_nop 0
	global_load_lds_dwordx4 v[158:159], off
	v_lshl_add_u64 v[158:159], v[188:189], 0, s[24:25]
	s_mov_b32 m0, s8
	s_nop 0
	global_load_lds_dwordx4 v[158:159], off
	v_lshl_add_u64 v[158:159], v[224:225], 0, s[24:25]
	s_mov_b32 m0, s12
	s_nop 0
	global_load_lds_dwordx4 v[158:159], off
	s_waitcnt vmcnt(8)
	s_waitcnt lgkmcnt(0)
	s_barrier
	s_setprio 3
	s_waitcnt lgkmcnt(0)
	v_mfma_f32_16x16x32_bf16 v[62:65], v[114:117], v[180:183], v[62:65]
	v_mfma_f32_16x16x32_bf16 v[58:61], v[130:133], v[180:183], v[58:61]
	v_mfma_f32_16x16x32_bf16 v[46:49], v[114:117], v[194:197], v[46:49]
	v_mfma_f32_16x16x32_bf16 v[42:45], v[130:133], v[194:197], v[42:45]
	v_mfma_f32_16x16x32_bf16 v[28:31], v[114:117], v[202:205], v[28:31]
	v_mfma_f32_16x16x32_bf16 v[24:27], v[130:133], v[202:205], v[24:27]
	v_mfma_f32_16x16x32_bf16 v[12:15], v[114:117], v[210:213], v[12:15]
	v_mfma_f32_16x16x32_bf16 v[8:11], v[130:133], v[210:213], v[8:11]
	v_mfma_f32_16x16x32_bf16 v[62:65], v[122:125], v[184:187], v[62:65]
	v_mfma_f32_16x16x32_bf16 v[58:61], v[142:145], v[184:187], v[58:61]
	v_mfma_f32_16x16x32_bf16 v[46:49], v[122:125], v[198:201], v[46:49]
	v_mfma_f32_16x16x32_bf16 v[42:45], v[142:145], v[198:201], v[42:45]
	v_mfma_f32_16x16x32_bf16 v[28:31], v[122:125], v[206:209], v[28:31]
	v_mfma_f32_16x16x32_bf16 v[24:27], v[142:145], v[206:209], v[24:27]
	v_mfma_f32_16x16x32_bf16 v[12:15], v[122:125], v[220:223], v[12:15]
	v_mfma_f32_16x16x32_bf16 v[8:11], v[142:145], v[220:223], v[8:11]
	s_setprio 0
	s_setprio 3
	v_mfma_f32_16x16x32_bf16 v[54:57], v[146:149], v[180:183], v[54:57]
	v_mfma_f32_16x16x32_bf16 v[50:53], v[172:175], v[180:183], v[50:53]
	v_mfma_f32_16x16x32_bf16 v[38:41], v[146:149], v[194:197], v[38:41]
	v_mfma_f32_16x16x32_bf16 v[34:37], v[172:175], v[194:197], v[34:37]
	v_mfma_f32_16x16x32_bf16 v[20:23], v[146:149], v[202:205], v[20:23]
	v_mfma_f32_16x16x32_bf16 v[16:19], v[172:175], v[202:205], v[16:19]
	v_mfma_f32_16x16x32_bf16 v[4:7], v[146:149], v[210:213], v[4:7]
	v_mfma_f32_16x16x32_bf16 v[0:3], v[172:175], v[210:213], v[0:3]
	v_mfma_f32_16x16x32_bf16 v[54:57], v[150:153], v[184:187], v[54:57]
	v_mfma_f32_16x16x32_bf16 v[50:53], v[176:179], v[184:187], v[50:53]
	v_mfma_f32_16x16x32_bf16 v[38:41], v[150:153], v[198:201], v[38:41]
	v_mfma_f32_16x16x32_bf16 v[34:37], v[176:179], v[198:201], v[34:37]
	v_mfma_f32_16x16x32_bf16 v[20:23], v[150:153], v[206:209], v[20:23]
	v_mfma_f32_16x16x32_bf16 v[16:19], v[176:179], v[206:209], v[16:19]
	v_mfma_f32_16x16x32_bf16 v[4:7], v[150:153], v[220:223], v[4:7]
	v_mfma_f32_16x16x32_bf16 v[0:3], v[176:179], v[220:223], v[0:3]
	s_setprio 0
	s_barrier
	s_add_i32 s54, s54, 2
	s_add_u32 s50, s50, 0x100
	s_addc_u32 s51, s51, 0
	s_add_u32 s43, s43, 0x100
	s_addc_u32 s45, s45, 0
	s_cmp_gt_u32 s54, 13
	s_cbranch_scc0 .LBB0_1424
	s_and_b64 vcc, exec, s[40:41]
	s_cbranch_vccz .LBB0_1427
	s_barrier

.LBB0_1688:
	s_add_u32 s0, s46, s38
	s_addc_u32 s1, s47, s39
	s_add_u32 s0, s0, 0x100
	s_addc_u32 s1, s1, 0
	s_add_u32 s59, s12, s38
	s_addc_u32 s61, s21, s39
	s_add_i32 s66, 0, 0x10000
	s_cmpk_eq_i32 s38, 0x700
	s_cselect_b32 s3, s19, s1
	s_cselect_b32 s2, s20, s0
	v_add_u32_e32 v32, s66, v184
	s_cselect_b32 s1, s23, s61
	s_cselect_b32 s0, s40, s59
	s_add_i32 s59, 0, 0x14000
	ds_read_b128 v[134:137], v32
	ds_read_b128 v[162:165], v32 offset:1024
	ds_read_b128 v[166:169], v32 offset:2048
	ds_read_b128 v[170:173], v32 offset:3072
	v_add_u32_e32 v32, s59, v184
	ds_read_b128 v[174:177], v32
	ds_read_b128 v[178:181], v32 offset:1024
	ds_read_b128 v[188:191], v32 offset:2048
	ds_read_b128 v[192:195], v32 offset:3072
	v_lshl_add_u64 v[152:153], v[130:131], 0, s[38:39]
	s_add_i32 m0, s7, 0xc000
	ds_read_b128 v[196:199], v187
	ds_read_b128 v[200:203], v187 offset:1024
	ds_read_b128 v[204:207], v187 offset:2048
	ds_read_b128 v[208:211], v187 offset:3072
	ds_read_b128 v[220:223], v187 offset:4096
	ds_read_b128 v[224:227], v187 offset:5120
	ds_read_b128 v[228:231], v187 offset:6144
	ds_read_b128 v[232:235], v187 offset:7168
	global_load_lds_dwordx4 v[152:153], off
	v_lshl_add_u64 v[152:153], v[132:133], 0, s[38:39]
	s_add_i32 m0, s7, 0xe000
	s_nop 0
	global_load_lds_dwordx4 v[152:153], off
	s_waitcnt vmcnt(8)
	s_waitcnt lgkmcnt(0)
	s_barrier
	s_setprio 3
	s_waitcnt lgkmcnt(0)
	v_mfma_f32_16x16x32_bf16 v[126:129], v[134:137], v[196:199], v[126:129]
	v_mfma_f32_16x16x32_bf16 v[122:125], v[166:169], v[196:199], v[122:125]
	v_mfma_f32_16x16x32_bf16 v[118:121], v[134:137], v[204:207], v[118:121]
	v_mfma_f32_16x16x32_bf16 v[114:117], v[166:169], v[204:207], v[114:117]
	v_mfma_f32_16x16x32_bf16 v[110:113], v[134:137], v[220:223], v[110:113]
	v_mfma_f32_16x16x32_bf16 v[106:109], v[166:169], v[220:223], v[106:109]
	v_mfma_f32_16x16x32_bf16 v[102:105], v[134:137], v[228:231], v[102:105]
	v_mfma_f32_16x16x32_bf16 v[98:101], v[166:169], v[228:231], v[98:101]
	v_mfma_f32_16x16x32_bf16 v[126:129], v[162:165], v[200:203], v[126:129]
	v_mfma_f32_16x16x32_bf16 v[122:125], v[170:173], v[200:203], v[122:125]
	v_mfma_f32_16x16x32_bf16 v[118:121], v[162:165], v[208:211], v[118:121]
	v_mfma_f32_16x16x32_bf16 v[114:117], v[170:173], v[208:211], v[114:117]
	v_mfma_f32_16x16x32_bf16 v[110:113], v[162:165], v[224:227], v[110:113]
	v_mfma_f32_16x16x32_bf16 v[106:109], v[170:173], v[224:227], v[106:109]
	v_mfma_f32_16x16x32_bf16 v[102:105], v[162:165], v[232:235], v[102:105]
	v_mfma_f32_16x16x32_bf16 v[98:101], v[170:173], v[232:235], v[98:101]
	s_setprio 0
	s_setprio 3
	v_mfma_f32_16x16x32_bf16 v[94:97], v[174:177], v[196:199], v[94:97]
	v_mfma_f32_16x16x32_bf16 v[90:93], v[188:191], v[196:199], v[90:93]
	v_mfma_f32_16x16x32_bf16 v[86:89], v[174:177], v[204:207], v[86:89]
	v_mfma_f32_16x16x32_bf16 v[82:85], v[188:191], v[204:207], v[82:85]
	v_mfma_f32_16x16x32_bf16 v[78:81], v[174:177], v[220:223], v[78:81]
	v_mfma_f32_16x16x32_bf16 v[74:77], v[188:191], v[220:223], v[74:77]
	v_mfma_f32_16x16x32_bf16 v[70:73], v[174:177], v[228:231], v[70:73]
	v_mfma_f32_16x16x32_bf16 v[66:69], v[188:191], v[228:231], v[66:69]
	v_mfma_f32_16x16x32_bf16 v[94:97], v[178:181], v[200:203], v[94:97]
	v_mfma_f32_16x16x32_bf16 v[90:93], v[192:195], v[200:203], v[90:93]
	v_mfma_f32_16x16x32_bf16 v[86:89], v[178:181], v[208:211], v[86:89]
	v_mfma_f32_16x16x32_bf16 v[82:85], v[192:195], v[208:211], v[82:85]
	v_mfma_f32_16x16x32_bf16 v[78:81], v[178:181], v[224:227], v[78:81]
	v_mfma_f32_16x16x32_bf16 v[74:77], v[192:195], v[224:227], v[74:77]
	v_mfma_f32_16x16x32_bf16 v[70:73], v[178:181], v[232:235], v[70:73]
	v_mfma_f32_16x16x32_bf16 v[66:69], v[192:195], v[232:235], v[66:69]
	s_setprio 0
	s_barrier
	s_add_i32 s61, s66, s18
	v_lshl_add_u64 v[152:153], s[0:1], 0, v[142:143]
	s_mov_b32 m0, s61
	ds_read_b128 v[196:199], v187 offset:16384
	ds_read_b128 v[200:203], v187 offset:17408
	ds_read_b128 v[204:207], v187 offset:18432
	ds_read_b128 v[208:211], v187 offset:19456
	ds_read_b128 v[220:223], v187 offset:20480
	ds_read_b128 v[224:227], v187 offset:21504
	ds_read_b128 v[228:231], v187 offset:22528
	ds_read_b128 v[232:235], v187 offset:23552
	global_load_lds_dwordx4 v[152:153], off
	s_add_i32 m0, s61, 0x2000
	s_add_u32 s66, s0, 0x40000
	v_lshl_add_u64 v[212:213], s[0:1], 0, v[138:139]
	s_addc_u32 s67, s1, 0
	s_add_i32 s59, s59, s18
	global_load_lds_dwordx4 v[212:213], off
	v_lshl_add_u64 v[236:237], s[66:67], 0, v[142:143]
	s_mov_b32 m0, s59
	v_lshl_add_u64 v[238:239], s[2:3], 0, v[140:141]
	global_load_lds_dwordx4 v[236:237], off
	v_lshl_add_u64 v[236:237], s[66:67], 0, v[138:139]
	s_add_i32 m0, s59, 0x2000
	s_nop 0
	global_load_lds_dwordx4 v[236:237], off
	v_lshl_add_u64 v[236:237], s[2:3], 0, v[144:145]
	s_mov_b32 m0, s7
	s_nop 0
	global_load_lds_dwordx4 v[236:237], off
	s_mov_b32 m0, s30
	s_nop 0
	global_load_lds_dwordx4 v[238:239], off
	s_waitcnt vmcnt(8)
	s_waitcnt lgkmcnt(0)
	s_barrier
	s_setprio 3
	s_waitcnt lgkmcnt(0)
	v_mfma_f32_16x16x32_bf16 v[62:65], v[134:137], v[196:199], v[62:65]
	v_mfma_f32_16x16x32_bf16 v[58:61], v[166:169], v[196:199], v[58:61]
	v_mfma_f32_16x16x32_bf16 v[54:57], v[134:137], v[204:207], v[54:57]
	v_mfma_f32_16x16x32_bf16 v[50:53], v[166:169], v[204:207], v[50:53]
	v_mfma_f32_16x16x32_bf16 v[46:49], v[134:137], v[220:223], v[46:49]
	v_mfma_f32_16x16x32_bf16 v[42:45], v[166:169], v[220:223], v[42:45]
	v_mfma_f32_16x16x32_bf16 v[38:41], v[134:137], v[228:231], v[38:41]
	v_mfma_f32_16x16x32_bf16 v[34:37], v[166:169], v[228:231], v[34:37]
	v_mfma_f32_16x16x32_bf16 v[62:65], v[162:165], v[200:203], v[62:65]
	v_mfma_f32_16x16x32_bf16 v[58:61], v[170:173], v[200:203], v[58:61]
	v_mfma_f32_16x16x32_bf16 v[54:57], v[162:165], v[208:211], v[54:57]
	v_mfma_f32_16x16x32_bf16 v[50:53], v[170:173], v[208:211], v[50:53]
	v_mfma_f32_16x16x32_bf16 v[46:49], v[162:165], v[224:227], v[46:49]
	v_mfma_f32_16x16x32_bf16 v[42:45], v[170:173], v[224:227], v[42:45]
	v_mfma_f32_16x16x32_bf16 v[38:41], v[162:165], v[232:235], v[38:41]
	v_mfma_f32_16x16x32_bf16 v[34:37], v[170:173], v[232:235], v[34:37]
	s_setprio 0
	s_setprio 3
	v_mfma_f32_16x16x32_bf16 v[28:31], v[174:177], v[196:199], v[28:31]
	v_mfma_f32_16x16x32_bf16 v[24:27], v[188:191], v[196:199], v[24:27]
	v_mfma_f32_16x16x32_bf16 v[20:23], v[174:177], v[204:207], v[20:23]
	v_mfma_f32_16x16x32_bf16 v[16:19], v[188:191], v[204:207], v[16:19]
	v_mfma_f32_16x16x32_bf16 v[12:15], v[174:177], v[220:223], v[12:15]
	v_mfma_f32_16x16x32_bf16 v[8:11], v[188:191], v[220:223], v[8:11]
	v_mfma_f32_16x16x32_bf16 v[4:7], v[174:177], v[228:231], v[4:7]
	v_mfma_f32_16x16x32_bf16 v[0:3], v[188:191], v[228:231], v[0:3]
	v_mfma_f32_16x16x32_bf16 v[28:31], v[178:181], v[200:203], v[28:31]
	v_mfma_f32_16x16x32_bf16 v[24:27], v[192:195], v[200:203], v[24:27]
	v_mfma_f32_16x16x32_bf16 v[20:23], v[178:181], v[208:211], v[20:23]
	v_mfma_f32_16x16x32_bf16 v[16:19], v[192:195], v[208:211], v[16:19]
	v_mfma_f32_16x16x32_bf16 v[12:15], v[178:181], v[224:227], v[12:15]
	v_mfma_f32_16x16x32_bf16 v[8:11], v[192:195], v[224:227], v[8:11]
	v_mfma_f32_16x16x32_bf16 v[4:7], v[178:181], v[232:235], v[4:7]
	v_mfma_f32_16x16x32_bf16 v[0:3], v[192:195], v[232:235], v[0:3]
	s_setprio 0
	s_barrier
	s_add_i32 s59, 0, 0x18000
	v_add_u32_e32 v32, s59, v184
	s_add_i32 s61, 0, 0x1c000
	ds_read_b128 v[134:137], v32
	ds_read_b128 v[162:165], v32 offset:1024
	ds_read_b128 v[166:169], v32 offset:2048
	ds_read_b128 v[170:173], v32 offset:3072
	v_add_u32_e32 v32, s61, v184
	ds_read_b128 v[174:177], v32
	ds_read_b128 v[178:181], v32 offset:1024
	ds_read_b128 v[188:191], v32 offset:2048
	ds_read_b128 v[192:195], v32 offset:3072
	s_add_u32 s2, s2, 0x40000
	s_addc_u32 s3, s3, 0
	s_mov_b32 m0, s31
	v_lshl_add_u64 v[240:241], s[2:3], 0, v[144:145]
	ds_read_b128 v[196:199], v187 offset:32768
	ds_read_b128 v[200:203], v187 offset:33792
	ds_read_b128 v[204:207], v187 offset:34816
	ds_read_b128 v[208:211], v187 offset:35840
	ds_read_b128 v[220:223], v187 offset:36864
	ds_read_b128 v[224:227], v187 offset:37888
	ds_read_b128 v[228:231], v187 offset:38912
	ds_read_b128 v[232:235], v187 offset:39936
	global_load_lds_dwordx4 v[240:241], off
	v_lshl_add_u64 v[240:241], s[2:3], 0, v[140:141]
	s_mov_b32 m0, s43
	s_nop 0
	global_load_lds_dwordx4 v[240:241], off
	s_waitcnt vmcnt(8)
	s_waitcnt lgkmcnt(0)
	s_barrier
	s_setprio 3
	s_waitcnt lgkmcnt(0)
	v_mfma_f32_16x16x32_bf16 v[126:129], v[134:137], v[196:199], v[126:129]
	v_mfma_f32_16x16x32_bf16 v[122:125], v[166:169], v[196:199], v[122:125]
	v_mfma_f32_16x16x32_bf16 v[118:121], v[134:137], v[204:207], v[118:121]
	v_mfma_f32_16x16x32_bf16 v[114:117], v[166:169], v[204:207], v[114:117]
	v_mfma_f32_16x16x32_bf16 v[110:113], v[134:137], v[220:223], v[110:113]
	v_mfma_f32_16x16x32_bf16 v[106:109], v[166:169], v[220:223], v[106:109]
	v_mfma_f32_16x16x32_bf16 v[102:105], v[134:137], v[228:231], v[102:105]
	v_mfma_f32_16x16x32_bf16 v[98:101], v[166:169], v[228:231], v[98:101]
	v_mfma_f32_16x16x32_bf16 v[126:129], v[162:165], v[200:203], v[126:129]
	v_mfma_f32_16x16x32_bf16 v[122:125], v[170:173], v[200:203], v[122:125]
	v_mfma_f32_16x16x32_bf16 v[118:121], v[162:165], v[208:211], v[118:121]
	v_mfma_f32_16x16x32_bf16 v[114:117], v[170:173], v[208:211], v[114:117]
	v_mfma_f32_16x16x32_bf16 v[110:113], v[162:165], v[224:227], v[110:113]
	v_mfma_f32_16x16x32_bf16 v[106:109], v[170:173], v[224:227], v[106:109]
	v_mfma_f32_16x16x32_bf16 v[102:105], v[162:165], v[232:235], v[102:105]
	v_mfma_f32_16x16x32_bf16 v[98:101], v[170:173], v[232:235], v[98:101]
	s_setprio 0
	s_setprio 3
	v_mfma_f32_16x16x32_bf16 v[94:97], v[174:177], v[196:199], v[94:97]
	v_mfma_f32_16x16x32_bf16 v[90:93], v[188:191], v[196:199], v[90:93]
	v_mfma_f32_16x16x32_bf16 v[86:89], v[174:177], v[204:207], v[86:89]
	v_mfma_f32_16x16x32_bf16 v[82:85], v[188:191], v[204:207], v[82:85]
	v_mfma_f32_16x16x32_bf16 v[78:81], v[174:177], v[220:223], v[78:81]
	v_mfma_f32_16x16x32_bf16 v[74:77], v[188:191], v[220:223], v[74:77]
	v_mfma_f32_16x16x32_bf16 v[70:73], v[174:177], v[228:231], v[70:73]
	v_mfma_f32_16x16x32_bf16 v[66:69], v[188:191], v[228:231], v[66:69]
	v_mfma_f32_16x16x32_bf16 v[94:97], v[178:181], v[200:203], v[94:97]
	v_mfma_f32_16x16x32_bf16 v[90:93], v[192:195], v[200:203], v[90:93]
	v_mfma_f32_16x16x32_bf16 v[86:89], v[178:181], v[208:211], v[86:89]
	v_mfma_f32_16x16x32_bf16 v[82:85], v[192:195], v[208:211], v[82:85]
	v_mfma_f32_16x16x32_bf16 v[78:81], v[178:181], v[224:227], v[78:81]
	v_mfma_f32_16x16x32_bf16 v[74:77], v[192:195], v[224:227], v[74:77]
	v_mfma_f32_16x16x32_bf16 v[70:73], v[178:181], v[232:235], v[70:73]
	v_mfma_f32_16x16x32_bf16 v[66:69], v[192:195], v[232:235], v[66:69]
	s_setprio 0
	s_barrier
	s_add_i32 s2, s59, s18
	v_lshl_add_u64 v[152:153], v[152:153], 0, s[24:25]
	s_mov_b32 m0, s2
	ds_read_b128 v[196:199], v187 offset:49152
	ds_read_b128 v[200:203], v187 offset:50176
	ds_read_b128 v[204:207], v187 offset:51200
	ds_read_b128 v[208:211], v187 offset:52224
	ds_read_b128 v[220:223], v187 offset:53248
	ds_read_b128 v[224:227], v187 offset:54272
	ds_read_b128 v[228:231], v187 offset:55296
	ds_read_b128 v[232:235], v187 offset:56320
	global_load_lds_dwordx4 v[152:153], off
	s_add_i32 m0, s2, 0x2000
	s_add_u32 s0, s0, 0x40080
	v_lshl_add_u64 v[152:153], v[212:213], 0, s[24:25]
	s_addc_u32 s1, s1, 0
	s_add_i32 s2, s61, s18
	global_load_lds_dwordx4 v[152:153], off
	v_lshl_add_u64 v[152:153], s[0:1], 0, v[142:143]
	s_mov_b32 m0, s2
	s_nop 0
	global_load_lds_dwordx4 v[152:153], off
	v_lshl_add_u64 v[152:153], s[0:1], 0, v[138:139]
	s_add_i32 m0, s2, 0x2000
	s_nop 0
	global_load_lds_dwordx4 v[152:153], off
	v_lshl_add_u64 v[152:153], v[236:237], 0, s[24:25]
	s_mov_b32 m0, s68
	s_nop 0
	global_load_lds_dwordx4 v[152:153], off
	v_lshl_add_u64 v[152:153], v[238:239], 0, s[24:25]
	s_mov_b32 m0, s69
	s_nop 0
	global_load_lds_dwordx4 v[152:153], off
	s_waitcnt vmcnt(8)
	s_waitcnt lgkmcnt(0)
	s_barrier
	s_setprio 3
	s_waitcnt lgkmcnt(0)
	v_mfma_f32_16x16x32_bf16 v[62:65], v[134:137], v[196:199], v[62:65]
	v_mfma_f32_16x16x32_bf16 v[58:61], v[166:169], v[196:199], v[58:61]
	v_mfma_f32_16x16x32_bf16 v[54:57], v[134:137], v[204:207], v[54:57]
	v_mfma_f32_16x16x32_bf16 v[50:53], v[166:169], v[204:207], v[50:53]
	v_mfma_f32_16x16x32_bf16 v[46:49], v[134:137], v[220:223], v[46:49]
	v_mfma_f32_16x16x32_bf16 v[42:45], v[166:169], v[220:223], v[42:45]
	v_mfma_f32_16x16x32_bf16 v[38:41], v[134:137], v[228:231], v[38:41]
	v_mfma_f32_16x16x32_bf16 v[34:37], v[166:169], v[228:231], v[34:37]
	v_mfma_f32_16x16x32_bf16 v[62:65], v[162:165], v[200:203], v[62:65]
	v_mfma_f32_16x16x32_bf16 v[58:61], v[170:173], v[200:203], v[58:61]
	v_mfma_f32_16x16x32_bf16 v[54:57], v[162:165], v[208:211], v[54:57]
	v_mfma_f32_16x16x32_bf16 v[50:53], v[170:173], v[208:211], v[50:53]
	v_mfma_f32_16x16x32_bf16 v[46:49], v[162:165], v[224:227], v[46:49]
	v_mfma_f32_16x16x32_bf16 v[42:45], v[170:173], v[224:227], v[42:45]
	v_mfma_f32_16x16x32_bf16 v[38:41], v[162:165], v[232:235], v[38:41]
	v_mfma_f32_16x16x32_bf16 v[34:37], v[170:173], v[232:235], v[34:37]
	s_setprio 0
	s_setprio 3
	v_mfma_f32_16x16x32_bf16 v[28:31], v[174:177], v[196:199], v[28:31]
	v_mfma_f32_16x16x32_bf16 v[24:27], v[188:191], v[196:199], v[24:27]
	v_mfma_f32_16x16x32_bf16 v[20:23], v[174:177], v[204:207], v[20:23]
	v_mfma_f32_16x16x32_bf16 v[16:19], v[188:191], v[204:207], v[16:19]
	v_mfma_f32_16x16x32_bf16 v[12:15], v[174:177], v[220:223], v[12:15]
	v_mfma_f32_16x16x32_bf16 v[8:11], v[188:191], v[220:223], v[8:11]
	v_mfma_f32_16x16x32_bf16 v[4:7], v[174:177], v[228:231], v[4:7]
	v_mfma_f32_16x16x32_bf16 v[0:3], v[188:191], v[228:231], v[0:3]
	v_mfma_f32_16x16x32_bf16 v[28:31], v[178:181], v[200:203], v[28:31]
	v_mfma_f32_16x16x32_bf16 v[24:27], v[192:195], v[200:203], v[24:27]
	v_mfma_f32_16x16x32_bf16 v[20:23], v[178:181], v[208:211], v[20:23]
	v_mfma_f32_16x16x32_bf16 v[16:19], v[192:195], v[208:211], v[16:19]
	v_mfma_f32_16x16x32_bf16 v[12:15], v[178:181], v[224:227], v[12:15]
	v_mfma_f32_16x16x32_bf16 v[8:11], v[192:195], v[224:227], v[8:11]
	v_mfma_f32_16x16x32_bf16 v[4:7], v[178:181], v[232:235], v[4:7]
	v_mfma_f32_16x16x32_bf16 v[0:3], v[192:195], v[232:235], v[0:3]
	s_setprio 0
	s_barrier
	s_add_i32 s41, s41, 2
	s_add_u32 s38, s38, 0x100
	s_addc_u32 s39, s39, 0
	s_cmp_gt_u32 s41, 13
	s_cbranch_scc0 .LBB0_1688
	s_and_b64 vcc, exec, s[56:57]
	s_cbranch_vccz .LBB0_1691
	s_barrier

.LBB0_2226:
	s_add_u32 s0, s50, 0xfffc0080
	s_addc_u32 s1, s51, -1
	s_add_i32 s55, 0, 0x10000
	s_cmp_eq_u32 s54, 12
	s_cselect_b32 s3, s21, s1
	s_cselect_b32 s2, s23, s0
	s_cselect_b32 s1, s43, s53
	s_cselect_b32 s0, s45, s52
	s_add_i32 s58, 0, 0x14000
	v_add_u32_e32 v142, s55, v191
	v_add_u32_e32 v158, s58, v191
	ds_read_b128 v[114:117], v142
	ds_read_b128 v[122:125], v142 offset:1024
	ds_read_b128 v[130:133], v142 offset:2048
	ds_read_b128 v[142:145], v142 offset:3072
	ds_read_b128 v[146:149], v158
	ds_read_b128 v[150:153], v158 offset:1024
	ds_read_b128 v[172:175], v158 offset:2048
	ds_read_b128 v[176:179], v158 offset:3072
	v_lshl_add_u64 v[188:189], s[50:51], 0, v[32:33]
	s_add_i32 m0, s30, 0xc000
	ds_read_b128 v[180:183], v193
	ds_read_b128 v[184:187], v193 offset:1024
	ds_read_b128 v[194:197], v193 offset:2048
	ds_read_b128 v[198:201], v193 offset:3072
	ds_read_b128 v[202:205], v193 offset:4096
	ds_read_b128 v[206:209], v193 offset:5120
	ds_read_b128 v[210:213], v193 offset:6144
	ds_read_b128 v[220:223], v193 offset:7168
	global_load_lds_dwordx4 v[188:189], off
	v_lshl_add_u64 v[188:189], s[50:51], 0, v[170:171]
	s_add_i32 m0, s30, 0xe000
	s_nop 0
	global_load_lds_dwordx4 v[188:189], off
	s_waitcnt vmcnt(8)
	s_waitcnt lgkmcnt(0)
	s_barrier
	s_setprio 3
	s_waitcnt lgkmcnt(0)
	v_mfma_f32_16x16x32_bf16 v[138:141], v[114:117], v[180:183], v[138:141]
	v_mfma_f32_16x16x32_bf16 v[134:137], v[130:133], v[180:183], v[134:137]
	v_mfma_f32_16x16x32_bf16 v[110:113], v[114:117], v[194:197], v[110:113]
	v_mfma_f32_16x16x32_bf16 v[106:109], v[130:133], v[194:197], v[106:109]
	v_mfma_f32_16x16x32_bf16 v[94:97], v[114:117], v[202:205], v[94:97]
	v_mfma_f32_16x16x32_bf16 v[90:93], v[130:133], v[202:205], v[90:93]
	v_mfma_f32_16x16x32_bf16 v[78:81], v[114:117], v[210:213], v[78:81]
	v_mfma_f32_16x16x32_bf16 v[74:77], v[130:133], v[210:213], v[74:77]
	v_mfma_f32_16x16x32_bf16 v[138:141], v[122:125], v[184:187], v[138:141]
	v_mfma_f32_16x16x32_bf16 v[134:137], v[142:145], v[184:187], v[134:137]
	v_mfma_f32_16x16x32_bf16 v[110:113], v[122:125], v[198:201], v[110:113]
	v_mfma_f32_16x16x32_bf16 v[106:109], v[142:145], v[198:201], v[106:109]
	v_mfma_f32_16x16x32_bf16 v[94:97], v[122:125], v[206:209], v[94:97]
	v_mfma_f32_16x16x32_bf16 v[90:93], v[142:145], v[206:209], v[90:93]
	v_mfma_f32_16x16x32_bf16 v[78:81], v[122:125], v[220:223], v[78:81]
	v_mfma_f32_16x16x32_bf16 v[74:77], v[142:145], v[220:223], v[74:77]
	s_setprio 0
	s_setprio 3
	v_mfma_f32_16x16x32_bf16 v[126:129], v[146:149], v[180:183], v[126:129]
	v_mfma_f32_16x16x32_bf16 v[118:121], v[172:175], v[180:183], v[118:121]
	v_mfma_f32_16x16x32_bf16 v[102:105], v[146:149], v[194:197], v[102:105]
	v_mfma_f32_16x16x32_bf16 v[98:101], v[172:175], v[194:197], v[98:101]
	v_mfma_f32_16x16x32_bf16 v[86:89], v[146:149], v[202:205], v[86:89]
	v_mfma_f32_16x16x32_bf16 v[82:85], v[172:175], v[202:205], v[82:85]
	v_mfma_f32_16x16x32_bf16 v[70:73], v[146:149], v[210:213], v[70:73]
	v_mfma_f32_16x16x32_bf16 v[66:69], v[172:175], v[210:213], v[66:69]
	v_mfma_f32_16x16x32_bf16 v[126:129], v[150:153], v[184:187], v[126:129]
	v_mfma_f32_16x16x32_bf16 v[118:121], v[176:179], v[184:187], v[118:121]
	v_mfma_f32_16x16x32_bf16 v[102:105], v[150:153], v[198:201], v[102:105]
	v_mfma_f32_16x16x32_bf16 v[98:101], v[176:179], v[198:201], v[98:101]
	v_mfma_f32_16x16x32_bf16 v[86:89], v[150:153], v[206:209], v[86:89]
	v_mfma_f32_16x16x32_bf16 v[82:85], v[176:179], v[206:209], v[82:85]
	v_mfma_f32_16x16x32_bf16 v[70:73], v[150:153], v[220:223], v[70:73]
	v_mfma_f32_16x16x32_bf16 v[66:69], v[176:179], v[220:223], v[66:69]
	s_setprio 0
	s_barrier
	s_add_i32 s55, s55, s29
	v_lshl_add_u64 v[188:189], s[0:1], 0, v[166:167]
	s_mov_b32 m0, s55
	ds_read_b128 v[180:183], v193 offset:16384
	ds_read_b128 v[184:187], v193 offset:17408
	ds_read_b128 v[194:197], v193 offset:18432
	ds_read_b128 v[198:201], v193 offset:19456
	ds_read_b128 v[202:205], v193 offset:20480
	ds_read_b128 v[206:209], v193 offset:21504
	ds_read_b128 v[210:213], v193 offset:22528
	ds_read_b128 v[220:223], v193 offset:23552
	global_load_lds_dwordx4 v[188:189], off
	s_add_i32 m0, s55, 0x2000
	s_add_u32 s56, s0, 0x40000
	v_lshl_add_u64 v[224:225], s[0:1], 0, v[162:163]
	s_addc_u32 s57, s1, 0
	s_add_i32 s55, s58, s29
	global_load_lds_dwordx4 v[224:225], off
	v_lshl_add_u64 v[226:227], s[56:57], 0, v[166:167]
	s_mov_b32 m0, s55
	v_lshl_add_u64 v[228:229], s[2:3], 0, v[164:165]
	global_load_lds_dwordx4 v[226:227], off
	v_lshl_add_u64 v[226:227], s[56:57], 0, v[162:163]
	s_add_i32 m0, s55, 0x2000
	s_nop 0
	global_load_lds_dwordx4 v[226:227], off
	v_lshl_add_u64 v[226:227], s[2:3], 0, v[168:169]
	s_mov_b32 m0, s30
	s_nop 0
	global_load_lds_dwordx4 v[226:227], off
	s_mov_b32 m0, s31
	s_nop 0
	global_load_lds_dwordx4 v[228:229], off
	s_waitcnt vmcnt(8)
	s_waitcnt lgkmcnt(0)
	s_barrier
	s_setprio 3
	s_waitcnt lgkmcnt(0)
	v_mfma_f32_16x16x32_bf16 v[62:65], v[114:117], v[180:183], v[62:65]
	v_mfma_f32_16x16x32_bf16 v[58:61], v[130:133], v[180:183], v[58:61]
	v_mfma_f32_16x16x32_bf16 v[46:49], v[114:117], v[194:197], v[46:49]
	v_mfma_f32_16x16x32_bf16 v[42:45], v[130:133], v[194:197], v[42:45]
	v_mfma_f32_16x16x32_bf16 v[28:31], v[114:117], v[202:205], v[28:31]
	v_mfma_f32_16x16x32_bf16 v[24:27], v[130:133], v[202:205], v[24:27]
	v_mfma_f32_16x16x32_bf16 v[12:15], v[114:117], v[210:213], v[12:15]
	v_mfma_f32_16x16x32_bf16 v[8:11], v[130:133], v[210:213], v[8:11]
	v_mfma_f32_16x16x32_bf16 v[62:65], v[122:125], v[184:187], v[62:65]
	v_mfma_f32_16x16x32_bf16 v[58:61], v[142:145], v[184:187], v[58:61]
	v_mfma_f32_16x16x32_bf16 v[46:49], v[122:125], v[198:201], v[46:49]
	v_mfma_f32_16x16x32_bf16 v[42:45], v[142:145], v[198:201], v[42:45]
	v_mfma_f32_16x16x32_bf16 v[28:31], v[122:125], v[206:209], v[28:31]
	v_mfma_f32_16x16x32_bf16 v[24:27], v[142:145], v[206:209], v[24:27]
	v_mfma_f32_16x16x32_bf16 v[12:15], v[122:125], v[220:223], v[12:15]
	v_mfma_f32_16x16x32_bf16 v[8:11], v[142:145], v[220:223], v[8:11]
	s_setprio 0
	s_setprio 3
	v_mfma_f32_16x16x32_bf16 v[54:57], v[146:149], v[180:183], v[54:57]
	v_mfma_f32_16x16x32_bf16 v[50:53], v[172:175], v[180:183], v[50:53]
	v_mfma_f32_16x16x32_bf16 v[38:41], v[146:149], v[194:197], v[38:41]
	v_mfma_f32_16x16x32_bf16 v[34:37], v[172:175], v[194:197], v[34:37]
	v_mfma_f32_16x16x32_bf16 v[20:23], v[146:149], v[202:205], v[20:23]
	v_mfma_f32_16x16x32_bf16 v[16:19], v[172:175], v[202:205], v[16:19]
	v_mfma_f32_16x16x32_bf16 v[4:7], v[146:149], v[210:213], v[4:7]
	v_mfma_f32_16x16x32_bf16 v[0:3], v[172:175], v[210:213], v[0:3]
	v_mfma_f32_16x16x32_bf16 v[54:57], v[150:153], v[184:187], v[54:57]
	v_mfma_f32_16x16x32_bf16 v[50:53], v[176:179], v[184:187], v[50:53]
	v_mfma_f32_16x16x32_bf16 v[38:41], v[150:153], v[198:201], v[38:41]
	v_mfma_f32_16x16x32_bf16 v[34:37], v[176:179], v[198:201], v[34:37]
	v_mfma_f32_16x16x32_bf16 v[20:23], v[150:153], v[206:209], v[20:23]
	v_mfma_f32_16x16x32_bf16 v[16:19], v[176:179], v[206:209], v[16:19]
	v_mfma_f32_16x16x32_bf16 v[4:7], v[150:153], v[220:223], v[4:7]
	v_mfma_f32_16x16x32_bf16 v[0:3], v[176:179], v[220:223], v[0:3]
	s_setprio 0
	s_barrier
	s_add_i32 s55, 0, 0x18000
	s_add_i32 s56, 0, 0x1c000
	v_add_u32_e32 v142, s55, v191
	v_add_u32_e32 v158, s56, v191
	ds_read_b128 v[114:117], v142
	ds_read_b128 v[122:125], v142 offset:1024
	ds_read_b128 v[130:133], v142 offset:2048
	ds_read_b128 v[142:145], v142 offset:3072
	ds_read_b128 v[146:149], v158
	ds_read_b128 v[150:153], v158 offset:1024
	ds_read_b128 v[172:175], v158 offset:2048
	ds_read_b128 v[176:179], v158 offset:3072
	s_add_u32 s2, s2, 0x40000
	s_addc_u32 s3, s3, 0
	s_mov_b32 m0, s62
	v_lshl_add_u64 v[230:231], s[2:3], 0, v[168:169]
	ds_read_b128 v[180:183], v193 offset:32768
	ds_read_b128 v[184:187], v193 offset:33792
	ds_read_b128 v[194:197], v193 offset:34816
	ds_read_b128 v[198:201], v193 offset:35840
	ds_read_b128 v[202:205], v193 offset:36864
	ds_read_b128 v[206:209], v193 offset:37888
	ds_read_b128 v[210:213], v193 offset:38912
	ds_read_b128 v[220:223], v193 offset:39936
	global_load_lds_dwordx4 v[230:231], off
	v_lshl_add_u64 v[230:231], s[2:3], 0, v[164:165]
	s_mov_b32 m0, s63
	s_nop 0
	global_load_lds_dwordx4 v[230:231], off
	s_waitcnt vmcnt(8)
	s_waitcnt lgkmcnt(0)
	s_barrier
	s_setprio 3
	s_waitcnt lgkmcnt(0)
	v_mfma_f32_16x16x32_bf16 v[138:141], v[114:117], v[180:183], v[138:141]
	v_mfma_f32_16x16x32_bf16 v[134:137], v[130:133], v[180:183], v[134:137]
	v_mfma_f32_16x16x32_bf16 v[110:113], v[114:117], v[194:197], v[110:113]
	v_mfma_f32_16x16x32_bf16 v[106:109], v[130:133], v[194:197], v[106:109]
	v_mfma_f32_16x16x32_bf16 v[94:97], v[114:117], v[202:205], v[94:97]
	v_mfma_f32_16x16x32_bf16 v[90:93], v[130:133], v[202:205], v[90:93]
	v_mfma_f32_16x16x32_bf16 v[78:81], v[114:117], v[210:213], v[78:81]
	v_mfma_f32_16x16x32_bf16 v[74:77], v[130:133], v[210:213], v[74:77]
	v_mfma_f32_16x16x32_bf16 v[138:141], v[122:125], v[184:187], v[138:141]
	v_mfma_f32_16x16x32_bf16 v[134:137], v[142:145], v[184:187], v[134:137]
	v_mfma_f32_16x16x32_bf16 v[110:113], v[122:125], v[198:201], v[110:113]
	v_mfma_f32_16x16x32_bf16 v[106:109], v[142:145], v[198:201], v[106:109]
	v_mfma_f32_16x16x32_bf16 v[94:97], v[122:125], v[206:209], v[94:97]
	v_mfma_f32_16x16x32_bf16 v[90:93], v[142:145], v[206:209], v[90:93]
	v_mfma_f32_16x16x32_bf16 v[78:81], v[122:125], v[220:223], v[78:81]
	v_mfma_f32_16x16x32_bf16 v[74:77], v[142:145], v[220:223], v[74:77]
	s_setprio 0
	s_setprio 3
	v_mfma_f32_16x16x32_bf16 v[126:129], v[146:149], v[180:183], v[126:129]
	v_mfma_f32_16x16x32_bf16 v[118:121], v[172:175], v[180:183], v[118:121]
	v_mfma_f32_16x16x32_bf16 v[102:105], v[146:149], v[194:197], v[102:105]
	v_mfma_f32_16x16x32_bf16 v[98:101], v[172:175], v[194:197], v[98:101]
	v_mfma_f32_16x16x32_bf16 v[86:89], v[146:149], v[202:205], v[86:89]
	v_mfma_f32_16x16x32_bf16 v[82:85], v[172:175], v[202:205], v[82:85]
	v_mfma_f32_16x16x32_bf16 v[70:73], v[146:149], v[210:213], v[70:73]
	v_mfma_f32_16x16x32_bf16 v[66:69], v[172:175], v[210:213], v[66:69]
	v_mfma_f32_16x16x32_bf16 v[126:129], v[150:153], v[184:187], v[126:129]
	v_mfma_f32_16x16x32_bf16 v[118:121], v[176:179], v[184:187], v[118:121]
	v_mfma_f32_16x16x32_bf16 v[102:105], v[150:153], v[198:201], v[102:105]
	v_mfma_f32_16x16x32_bf16 v[98:101], v[176:179], v[198:201], v[98:101]
	v_mfma_f32_16x16x32_bf16 v[86:89], v[150:153], v[206:209], v[86:89]
	v_mfma_f32_16x16x32_bf16 v[82:85], v[176:179], v[206:209], v[82:85]
	v_mfma_f32_16x16x32_bf16 v[70:73], v[150:153], v[220:223], v[70:73]
	v_mfma_f32_16x16x32_bf16 v[66:69], v[176:179], v[220:223], v[66:69]
	s_setprio 0
	s_barrier
	s_add_i32 s2, s55, s29
	v_lshl_add_u64 v[188:189], v[188:189], 0, s[24:25]
	s_mov_b32 m0, s2
	ds_read_b128 v[180:183], v193 offset:49152
	ds_read_b128 v[184:187], v193 offset:50176
	ds_read_b128 v[194:197], v193 offset:51200
	ds_read_b128 v[198:201], v193 offset:52224
	ds_read_b128 v[202:205], v193 offset:53248
	ds_read_b128 v[206:209], v193 offset:54272
	ds_read_b128 v[210:213], v193 offset:55296
	ds_read_b128 v[220:223], v193 offset:56320
	global_load_lds_dwordx4 v[188:189], off
	s_add_i32 m0, s2, 0x2000
	s_add_u32 s0, s0, 0x40080
	v_lshl_add_u64 v[188:189], v[224:225], 0, s[24:25]
	s_addc_u32 s1, s1, 0
	s_add_i32 s2, s56, s29
	global_load_lds_dwordx4 v[188:189], off
	v_lshl_add_u64 v[188:189], s[0:1], 0, v[166:167]
	s_mov_b32 m0, s2
	s_nop 0
	global_load_lds_dwordx4 v[188:189], off
	v_lshl_add_u64 v[188:189], s[0:1], 0, v[162:163]
	s_add_i32 m0, s2, 0x2000
	s_nop 0
	global_load_lds_dwordx4 v[188:189], off
	v_lshl_add_u64 v[188:189], v[226:227], 0, s[24:25]
	s_mov_b32 m0, s8
	s_nop 0
	global_load_lds_dwordx4 v[188:189], off
	v_lshl_add_u64 v[188:189], v[228:229], 0, s[24:25]
	s_mov_b32 m0, s12
	s_nop 0
	global_load_lds_dwordx4 v[188:189], off
	s_waitcnt vmcnt(8)
	s_waitcnt lgkmcnt(0)
	s_barrier
	s_setprio 3
	s_waitcnt lgkmcnt(0)
	v_mfma_f32_16x16x32_bf16 v[62:65], v[114:117], v[180:183], v[62:65]
	v_mfma_f32_16x16x32_bf16 v[58:61], v[130:133], v[180:183], v[58:61]
	v_mfma_f32_16x16x32_bf16 v[46:49], v[114:117], v[194:197], v[46:49]
	v_mfma_f32_16x16x32_bf16 v[42:45], v[130:133], v[194:197], v[42:45]
	v_mfma_f32_16x16x32_bf16 v[28:31], v[114:117], v[202:205], v[28:31]
	v_mfma_f32_16x16x32_bf16 v[24:27], v[130:133], v[202:205], v[24:27]
	v_mfma_f32_16x16x32_bf16 v[12:15], v[114:117], v[210:213], v[12:15]
	v_mfma_f32_16x16x32_bf16 v[8:11], v[130:133], v[210:213], v[8:11]
	v_mfma_f32_16x16x32_bf16 v[62:65], v[122:125], v[184:187], v[62:65]
	v_mfma_f32_16x16x32_bf16 v[58:61], v[142:145], v[184:187], v[58:61]
	v_mfma_f32_16x16x32_bf16 v[46:49], v[122:125], v[198:201], v[46:49]
	v_mfma_f32_16x16x32_bf16 v[42:45], v[142:145], v[198:201], v[42:45]
	v_mfma_f32_16x16x32_bf16 v[28:31], v[122:125], v[206:209], v[28:31]
	v_mfma_f32_16x16x32_bf16 v[24:27], v[142:145], v[206:209], v[24:27]
	v_mfma_f32_16x16x32_bf16 v[12:15], v[122:125], v[220:223], v[12:15]
	v_mfma_f32_16x16x32_bf16 v[8:11], v[142:145], v[220:223], v[8:11]
	s_setprio 0
	s_setprio 3
	v_mfma_f32_16x16x32_bf16 v[54:57], v[146:149], v[180:183], v[54:57]
	v_mfma_f32_16x16x32_bf16 v[50:53], v[172:175], v[180:183], v[50:53]
	v_mfma_f32_16x16x32_bf16 v[38:41], v[146:149], v[194:197], v[38:41]
	v_mfma_f32_16x16x32_bf16 v[34:37], v[172:175], v[194:197], v[34:37]
	v_mfma_f32_16x16x32_bf16 v[20:23], v[146:149], v[202:205], v[20:23]
	v_mfma_f32_16x16x32_bf16 v[16:19], v[172:175], v[202:205], v[16:19]
	v_mfma_f32_16x16x32_bf16 v[4:7], v[146:149], v[210:213], v[4:7]
	v_mfma_f32_16x16x32_bf16 v[0:3], v[172:175], v[210:213], v[0:3]
	v_mfma_f32_16x16x32_bf16 v[54:57], v[150:153], v[184:187], v[54:57]
	v_mfma_f32_16x16x32_bf16 v[50:53], v[176:179], v[184:187], v[50:53]
	v_mfma_f32_16x16x32_bf16 v[38:41], v[150:153], v[198:201], v[38:41]
	v_mfma_f32_16x16x32_bf16 v[34:37], v[176:179], v[198:201], v[34:37]
	v_mfma_f32_16x16x32_bf16 v[20:23], v[150:153], v[206:209], v[20:23]
	v_mfma_f32_16x16x32_bf16 v[16:19], v[176:179], v[206:209], v[16:19]
	v_mfma_f32_16x16x32_bf16 v[4:7], v[150:153], v[220:223], v[4:7]
	v_mfma_f32_16x16x32_bf16 v[0:3], v[176:179], v[220:223], v[0:3]
	s_setprio 0
	s_barrier
	s_add_i32 s54, s54, 2
	s_add_u32 s50, s50, 0x100
	s_addc_u32 s51, s51, 0
	s_add_u32 s52, s52, 0x100
	s_addc_u32 s53, s53, 0
	s_cmp_gt_u32 s54, 13
	s_cbranch_scc0 .LBB0_2226
	s_and_b64 vcc, exec, s[40:41]
	s_cbranch_vccz .LBB0_2229
	s_barrier

.LBB0_2536:
	s_add_u32 s2, s56, 0xfffc0080
	s_addc_u32 s3, s57, -1
	s_add_i32 s34, 0, 0x10000
	s_cmp_eq_u32 s31, 12
	s_cselect_b32 s3, s19, s3
	s_cselect_b32 s2, s21, s2
	v_add_u32_e32 v158, s34, v165
	s_cselect_b32 s43, s23, s30
	s_cselect_b32 s42, s28, s29
	s_add_i32 s41, 0, 0x14000
	ds_read_b128 v[142:145], v158
	ds_read_b128 v[146:149], v158 offset:1024
	ds_read_b128 v[150:153], v158 offset:2048
	ds_read_b128 v[176:179], v158 offset:3072
	v_add_u32_e32 v158, s41, v165
	ds_read_b128 v[180:183], v158
	ds_read_b128 v[184:187], v158 offset:1024
	ds_read_b128 v[188:191], v158 offset:2048
	ds_read_b128 v[192:195], v158 offset:3072
	v_lshl_add_u64 v[158:159], s[56:57], 0, v[32:33]
	s_add_i32 m0, s75, 0xc000
	ds_read_b128 v[196:199], v175
	ds_read_b128 v[200:203], v175 offset:1024
	ds_read_b128 v[204:207], v175 offset:2048
	ds_read_b128 v[208:211], v175 offset:3072
	ds_read_b128 v[220:223], v175 offset:4096
	ds_read_b128 v[224:227], v175 offset:5120
	ds_read_b128 v[228:231], v175 offset:6144
	ds_read_b128 v[232:235], v175 offset:7168
	global_load_lds_dwordx4 v[158:159], off
	v_lshl_add_u64 v[158:159], s[56:57], 0, v[140:141]
	s_add_i32 m0, s75, 0xe000
	s_nop 0
	global_load_lds_dwordx4 v[158:159], off
	s_waitcnt vmcnt(8)
	s_waitcnt lgkmcnt(0)
	s_barrier
	s_setprio 3
	s_waitcnt lgkmcnt(0)
	v_mfma_f32_16x16x32_bf16 v[126:129], v[142:145], v[196:199], v[126:129]
	v_mfma_f32_16x16x32_bf16 v[118:121], v[150:153], v[196:199], v[118:121]
	v_mfma_f32_16x16x32_bf16 v[110:113], v[142:145], v[204:207], v[110:113]
	v_mfma_f32_16x16x32_bf16 v[102:105], v[150:153], v[204:207], v[102:105]
	v_mfma_f32_16x16x32_bf16 v[94:97], v[142:145], v[220:223], v[94:97]
	v_mfma_f32_16x16x32_bf16 v[86:89], v[150:153], v[220:223], v[86:89]
	v_mfma_f32_16x16x32_bf16 v[78:81], v[142:145], v[228:231], v[78:81]
	v_mfma_f32_16x16x32_bf16 v[70:73], v[150:153], v[228:231], v[70:73]
	v_mfma_f32_16x16x32_bf16 v[126:129], v[146:149], v[200:203], v[126:129]
	v_mfma_f32_16x16x32_bf16 v[118:121], v[176:179], v[200:203], v[118:121]
	v_mfma_f32_16x16x32_bf16 v[110:113], v[146:149], v[208:211], v[110:113]
	v_mfma_f32_16x16x32_bf16 v[102:105], v[176:179], v[208:211], v[102:105]
	v_mfma_f32_16x16x32_bf16 v[94:97], v[146:149], v[224:227], v[94:97]
	v_mfma_f32_16x16x32_bf16 v[86:89], v[176:179], v[224:227], v[86:89]
	v_mfma_f32_16x16x32_bf16 v[78:81], v[146:149], v[232:235], v[78:81]
	v_mfma_f32_16x16x32_bf16 v[70:73], v[176:179], v[232:235], v[70:73]
	s_setprio 0
	s_setprio 3
	v_mfma_f32_16x16x32_bf16 v[122:125], v[180:183], v[196:199], v[122:125]
	v_mfma_f32_16x16x32_bf16 v[114:117], v[188:191], v[196:199], v[114:117]
	v_mfma_f32_16x16x32_bf16 v[106:109], v[180:183], v[204:207], v[106:109]
	v_mfma_f32_16x16x32_bf16 v[98:101], v[188:191], v[204:207], v[98:101]
	v_mfma_f32_16x16x32_bf16 v[90:93], v[180:183], v[220:223], v[90:93]
	v_mfma_f32_16x16x32_bf16 v[82:85], v[188:191], v[220:223], v[82:85]
	v_mfma_f32_16x16x32_bf16 v[74:77], v[180:183], v[228:231], v[74:77]
	v_mfma_f32_16x16x32_bf16 v[66:69], v[188:191], v[228:231], v[66:69]
	v_mfma_f32_16x16x32_bf16 v[122:125], v[184:187], v[200:203], v[122:125]
	v_mfma_f32_16x16x32_bf16 v[114:117], v[192:195], v[200:203], v[114:117]
	v_mfma_f32_16x16x32_bf16 v[106:109], v[184:187], v[208:211], v[106:109]
	v_mfma_f32_16x16x32_bf16 v[98:101], v[192:195], v[208:211], v[98:101]
	v_mfma_f32_16x16x32_bf16 v[90:93], v[184:187], v[224:227], v[90:93]
	v_mfma_f32_16x16x32_bf16 v[82:85], v[192:195], v[224:227], v[82:85]
	v_mfma_f32_16x16x32_bf16 v[74:77], v[184:187], v[232:235], v[74:77]
	v_mfma_f32_16x16x32_bf16 v[66:69], v[192:195], v[232:235], v[66:69]
	s_setprio 0
	s_barrier
	s_add_i32 s34, s34, s74
	v_lshl_add_u64 v[158:159], s[42:43], 0, v[134:135]
	s_mov_b32 m0, s34
	ds_read_b128 v[196:199], v175 offset:16384
	ds_read_b128 v[200:203], v175 offset:17408
	ds_read_b128 v[204:207], v175 offset:18432
	ds_read_b128 v[208:211], v175 offset:19456
	ds_read_b128 v[220:223], v175 offset:20480
	ds_read_b128 v[224:227], v175 offset:21504
	ds_read_b128 v[228:231], v175 offset:22528
	ds_read_b128 v[232:235], v175 offset:23552
	global_load_lds_dwordx4 v[158:159], off
	s_add_i32 m0, s34, 0x2000
	s_add_u32 s34, s42, 0x40000
	v_lshl_add_u64 v[160:161], s[42:43], 0, v[130:131]
	s_addc_u32 s35, s43, 0
	s_add_i32 s41, s41, s74
	global_load_lds_dwordx4 v[160:161], off
	v_lshl_add_u64 v[162:163], s[34:35], 0, v[134:135]
	s_mov_b32 m0, s41
	v_lshl_add_u64 v[212:213], s[2:3], 0, v[132:133]
	global_load_lds_dwordx4 v[162:163], off
	v_lshl_add_u64 v[162:163], s[34:35], 0, v[130:131]
	s_add_i32 m0, s41, 0x2000
	s_nop 0
	global_load_lds_dwordx4 v[162:163], off
	v_lshl_add_u64 v[162:163], s[2:3], 0, v[136:137]
	s_mov_b32 m0, s75
	s_nop 0
	global_load_lds_dwordx4 v[162:163], off
	s_mov_b32 m0, s76
	s_nop 0
	global_load_lds_dwordx4 v[212:213], off
	s_waitcnt vmcnt(8)
	s_waitcnt lgkmcnt(0)
	s_barrier
	s_setprio 3
	s_waitcnt lgkmcnt(0)
	v_mfma_f32_16x16x32_bf16 v[62:65], v[142:145], v[196:199], v[62:65]
	v_mfma_f32_16x16x32_bf16 v[54:57], v[150:153], v[196:199], v[54:57]
	v_mfma_f32_16x16x32_bf16 v[46:49], v[142:145], v[204:207], v[46:49]
	v_mfma_f32_16x16x32_bf16 v[38:41], v[150:153], v[204:207], v[38:41]
	v_mfma_f32_16x16x32_bf16 v[28:31], v[142:145], v[220:223], v[28:31]
	v_mfma_f32_16x16x32_bf16 v[20:23], v[150:153], v[220:223], v[20:23]
	v_mfma_f32_16x16x32_bf16 v[12:15], v[142:145], v[228:231], v[12:15]
	v_mfma_f32_16x16x32_bf16 v[4:7], v[150:153], v[228:231], v[4:7]
	v_mfma_f32_16x16x32_bf16 v[62:65], v[146:149], v[200:203], v[62:65]
	v_mfma_f32_16x16x32_bf16 v[54:57], v[176:179], v[200:203], v[54:57]
	v_mfma_f32_16x16x32_bf16 v[46:49], v[146:149], v[208:211], v[46:49]
	v_mfma_f32_16x16x32_bf16 v[38:41], v[176:179], v[208:211], v[38:41]
	v_mfma_f32_16x16x32_bf16 v[28:31], v[146:149], v[224:227], v[28:31]
	v_mfma_f32_16x16x32_bf16 v[20:23], v[176:179], v[224:227], v[20:23]
	v_mfma_f32_16x16x32_bf16 v[12:15], v[146:149], v[232:235], v[12:15]
	v_mfma_f32_16x16x32_bf16 v[4:7], v[176:179], v[232:235], v[4:7]
	s_setprio 0
	s_setprio 3
	v_mfma_f32_16x16x32_bf16 v[58:61], v[180:183], v[196:199], v[58:61]
	v_mfma_f32_16x16x32_bf16 v[50:53], v[188:191], v[196:199], v[50:53]
	v_mfma_f32_16x16x32_bf16 v[42:45], v[180:183], v[204:207], v[42:45]
	v_mfma_f32_16x16x32_bf16 v[34:37], v[188:191], v[204:207], v[34:37]
	v_mfma_f32_16x16x32_bf16 v[24:27], v[180:183], v[220:223], v[24:27]
	v_mfma_f32_16x16x32_bf16 v[16:19], v[188:191], v[220:223], v[16:19]
	v_mfma_f32_16x16x32_bf16 v[8:11], v[180:183], v[228:231], v[8:11]
	v_mfma_f32_16x16x32_bf16 v[0:3], v[188:191], v[228:231], v[0:3]
	v_mfma_f32_16x16x32_bf16 v[58:61], v[184:187], v[200:203], v[58:61]
	v_mfma_f32_16x16x32_bf16 v[50:53], v[192:195], v[200:203], v[50:53]
	v_mfma_f32_16x16x32_bf16 v[42:45], v[184:187], v[208:211], v[42:45]
	v_mfma_f32_16x16x32_bf16 v[34:37], v[192:195], v[208:211], v[34:37]
	v_mfma_f32_16x16x32_bf16 v[24:27], v[184:187], v[224:227], v[24:27]
	v_mfma_f32_16x16x32_bf16 v[16:19], v[192:195], v[224:227], v[16:19]
	v_mfma_f32_16x16x32_bf16 v[8:11], v[184:187], v[232:235], v[8:11]
	v_mfma_f32_16x16x32_bf16 v[0:3], v[192:195], v[232:235], v[0:3]
	s_setprio 0
	s_barrier
	s_add_i32 s34, 0, 0x18000
	s_add_i32 s35, 0, 0x1c000
	v_add_u32_e32 v176, s34, v165
	v_add_u32_e32 v192, s35, v165
	ds_read_b128 v[142:145], v176
	ds_read_b128 v[146:149], v176 offset:1024
	ds_read_b128 v[150:153], v176 offset:2048
	ds_read_b128 v[176:179], v176 offset:3072
	ds_read_b128 v[180:183], v192
	ds_read_b128 v[184:187], v192 offset:1024
	ds_read_b128 v[188:191], v192 offset:2048
	ds_read_b128 v[192:195], v192 offset:3072
	s_add_u32 s2, s2, 0x40000
	s_addc_u32 s3, s3, 0
	s_mov_b32 m0, s77
	v_lshl_add_u64 v[236:237], s[2:3], 0, v[136:137]
	ds_read_b128 v[196:199], v175 offset:32768
	ds_read_b128 v[200:203], v175 offset:33792
	ds_read_b128 v[204:207], v175 offset:34816
	ds_read_b128 v[208:211], v175 offset:35840
	ds_read_b128 v[220:223], v175 offset:36864
	ds_read_b128 v[224:227], v175 offset:37888
	ds_read_b128 v[228:231], v175 offset:38912
	ds_read_b128 v[232:235], v175 offset:39936
	global_load_lds_dwordx4 v[236:237], off
	v_lshl_add_u64 v[236:237], s[2:3], 0, v[132:133]
	s_mov_b32 m0, s78
	s_nop 0
	global_load_lds_dwordx4 v[236:237], off
	s_waitcnt vmcnt(8)
	s_waitcnt lgkmcnt(0)
	s_barrier
	s_setprio 3
	s_waitcnt lgkmcnt(0)
	v_mfma_f32_16x16x32_bf16 v[126:129], v[142:145], v[196:199], v[126:129]
	v_mfma_f32_16x16x32_bf16 v[118:121], v[150:153], v[196:199], v[118:121]
	v_mfma_f32_16x16x32_bf16 v[110:113], v[142:145], v[204:207], v[110:113]
	v_mfma_f32_16x16x32_bf16 v[102:105], v[150:153], v[204:207], v[102:105]
	v_mfma_f32_16x16x32_bf16 v[94:97], v[142:145], v[220:223], v[94:97]
	v_mfma_f32_16x16x32_bf16 v[86:89], v[150:153], v[220:223], v[86:89]
	v_mfma_f32_16x16x32_bf16 v[78:81], v[142:145], v[228:231], v[78:81]
	v_mfma_f32_16x16x32_bf16 v[70:73], v[150:153], v[228:231], v[70:73]
	v_mfma_f32_16x16x32_bf16 v[126:129], v[146:149], v[200:203], v[126:129]
	v_mfma_f32_16x16x32_bf16 v[118:121], v[176:179], v[200:203], v[118:121]
	v_mfma_f32_16x16x32_bf16 v[110:113], v[146:149], v[208:211], v[110:113]
	v_mfma_f32_16x16x32_bf16 v[102:105], v[176:179], v[208:211], v[102:105]
	v_mfma_f32_16x16x32_bf16 v[94:97], v[146:149], v[224:227], v[94:97]
	v_mfma_f32_16x16x32_bf16 v[86:89], v[176:179], v[224:227], v[86:89]
	v_mfma_f32_16x16x32_bf16 v[78:81], v[146:149], v[232:235], v[78:81]
	v_mfma_f32_16x16x32_bf16 v[70:73], v[176:179], v[232:235], v[70:73]
	s_setprio 0
	s_setprio 3
	v_mfma_f32_16x16x32_bf16 v[122:125], v[180:183], v[196:199], v[122:125]
	v_mfma_f32_16x16x32_bf16 v[114:117], v[188:191], v[196:199], v[114:117]
	v_mfma_f32_16x16x32_bf16 v[106:109], v[180:183], v[204:207], v[106:109]
	v_mfma_f32_16x16x32_bf16 v[98:101], v[188:191], v[204:207], v[98:101]
	v_mfma_f32_16x16x32_bf16 v[90:93], v[180:183], v[220:223], v[90:93]
	v_mfma_f32_16x16x32_bf16 v[82:85], v[188:191], v[220:223], v[82:85]
	v_mfma_f32_16x16x32_bf16 v[74:77], v[180:183], v[228:231], v[74:77]
	v_mfma_f32_16x16x32_bf16 v[66:69], v[188:191], v[228:231], v[66:69]
	v_mfma_f32_16x16x32_bf16 v[122:125], v[184:187], v[200:203], v[122:125]
	v_mfma_f32_16x16x32_bf16 v[114:117], v[192:195], v[200:203], v[114:117]
	v_mfma_f32_16x16x32_bf16 v[106:109], v[184:187], v[208:211], v[106:109]
	v_mfma_f32_16x16x32_bf16 v[98:101], v[192:195], v[208:211], v[98:101]
	v_mfma_f32_16x16x32_bf16 v[90:93], v[184:187], v[224:227], v[90:93]
	v_mfma_f32_16x16x32_bf16 v[82:85], v[192:195], v[224:227], v[82:85]
	v_mfma_f32_16x16x32_bf16 v[74:77], v[184:187], v[232:235], v[74:77]
	v_mfma_f32_16x16x32_bf16 v[66:69], v[192:195], v[232:235], v[66:69]
	s_setprio 0
	s_barrier
	s_add_i32 s2, s34, s74
	v_lshl_add_u64 v[158:159], v[158:159], 0, s[24:25]
	s_mov_b32 m0, s2
	ds_read_b128 v[196:199], v175 offset:49152
	ds_read_b128 v[200:203], v175 offset:50176
	ds_read_b128 v[204:207], v175 offset:51200
	ds_read_b128 v[208:211], v175 offset:52224
	ds_read_b128 v[220:223], v175 offset:53248
	ds_read_b128 v[224:227], v175 offset:54272
	ds_read_b128 v[228:231], v175 offset:55296
	ds_read_b128 v[232:235], v175 offset:56320
	global_load_lds_dwordx4 v[158:159], off
	s_add_i32 m0, s2, 0x2000
	s_add_u32 s2, s42, 0x40080
	v_lshl_add_u64 v[158:159], v[160:161], 0, s[24:25]
	s_addc_u32 s3, s43, 0
	s_add_i32 s34, s35, s74
	global_load_lds_dwordx4 v[158:159], off
	v_lshl_add_u64 v[158:159], s[2:3], 0, v[134:135]
	s_mov_b32 m0, s34
	s_nop 0
	global_load_lds_dwordx4 v[158:159], off
	v_lshl_add_u64 v[158:159], s[2:3], 0, v[130:131]
	s_add_i32 m0, s34, 0x2000
	s_nop 0
	global_load_lds_dwordx4 v[158:159], off
	v_lshl_add_u64 v[158:159], v[162:163], 0, s[24:25]
	s_mov_b32 m0, s8
	s_nop 0
	global_load_lds_dwordx4 v[158:159], off
	v_lshl_add_u64 v[158:159], v[212:213], 0, s[24:25]
	s_mov_b32 m0, s11
	s_nop 0
	global_load_lds_dwordx4 v[158:159], off
	s_waitcnt vmcnt(8)
	s_waitcnt lgkmcnt(0)
	s_barrier
	s_setprio 3
	s_waitcnt lgkmcnt(0)
	v_mfma_f32_16x16x32_bf16 v[62:65], v[142:145], v[196:199], v[62:65]
	v_mfma_f32_16x16x32_bf16 v[54:57], v[150:153], v[196:199], v[54:57]
	v_mfma_f32_16x16x32_bf16 v[46:49], v[142:145], v[204:207], v[46:49]
	v_mfma_f32_16x16x32_bf16 v[38:41], v[150:153], v[204:207], v[38:41]
	v_mfma_f32_16x16x32_bf16 v[28:31], v[142:145], v[220:223], v[28:31]
	v_mfma_f32_16x16x32_bf16 v[20:23], v[150:153], v[220:223], v[20:23]
	v_mfma_f32_16x16x32_bf16 v[12:15], v[142:145], v[228:231], v[12:15]
	v_mfma_f32_16x16x32_bf16 v[4:7], v[150:153], v[228:231], v[4:7]
	v_mfma_f32_16x16x32_bf16 v[62:65], v[146:149], v[200:203], v[62:65]
	v_mfma_f32_16x16x32_bf16 v[54:57], v[176:179], v[200:203], v[54:57]
	v_mfma_f32_16x16x32_bf16 v[46:49], v[146:149], v[208:211], v[46:49]
	v_mfma_f32_16x16x32_bf16 v[38:41], v[176:179], v[208:211], v[38:41]
	v_mfma_f32_16x16x32_bf16 v[28:31], v[146:149], v[224:227], v[28:31]
	v_mfma_f32_16x16x32_bf16 v[20:23], v[176:179], v[224:227], v[20:23]
	v_mfma_f32_16x16x32_bf16 v[12:15], v[146:149], v[232:235], v[12:15]
	v_mfma_f32_16x16x32_bf16 v[4:7], v[176:179], v[232:235], v[4:7]
	s_setprio 0
	s_setprio 3
	v_mfma_f32_16x16x32_bf16 v[58:61], v[180:183], v[196:199], v[58:61]
	v_mfma_f32_16x16x32_bf16 v[50:53], v[188:191], v[196:199], v[50:53]
	v_mfma_f32_16x16x32_bf16 v[42:45], v[180:183], v[204:207], v[42:45]
	v_mfma_f32_16x16x32_bf16 v[34:37], v[188:191], v[204:207], v[34:37]
	v_mfma_f32_16x16x32_bf16 v[24:27], v[180:183], v[220:223], v[24:27]
	v_mfma_f32_16x16x32_bf16 v[16:19], v[188:191], v[220:223], v[16:19]
	v_mfma_f32_16x16x32_bf16 v[8:11], v[180:183], v[228:231], v[8:11]
	v_mfma_f32_16x16x32_bf16 v[0:3], v[188:191], v[228:231], v[0:3]
	v_mfma_f32_16x16x32_bf16 v[58:61], v[184:187], v[200:203], v[58:61]
	v_mfma_f32_16x16x32_bf16 v[50:53], v[192:195], v[200:203], v[50:53]
	v_mfma_f32_16x16x32_bf16 v[42:45], v[184:187], v[208:211], v[42:45]
	v_mfma_f32_16x16x32_bf16 v[34:37], v[192:195], v[208:211], v[34:37]
	v_mfma_f32_16x16x32_bf16 v[24:27], v[184:187], v[224:227], v[24:27]
	v_mfma_f32_16x16x32_bf16 v[16:19], v[192:195], v[224:227], v[16:19]
	v_mfma_f32_16x16x32_bf16 v[8:11], v[184:187], v[232:235], v[8:11]
	v_mfma_f32_16x16x32_bf16 v[0:3], v[192:195], v[232:235], v[0:3]
	s_setprio 0
	s_barrier
	s_add_i32 s31, s31, 2
	s_add_u32 s56, s56, 0x100
	s_addc_u32 s57, s57, 0
	s_add_u32 s29, s29, 0x100
	s_addc_u32 s30, s30, 0
	s_cmp_gt_u32 s31, 13
	s_cbranch_scc0 .LBB0_2536
	s_and_b64 vcc, exec, s[38:39]
	s_cbranch_vccz .LBB0_2539
	s_barrier

.LBB0_2557:
	s_add_u32 s2, s56, 0xfffc0080
	s_addc_u32 s3, s57, -1
	s_add_i32 s34, 0, 0x10000
	s_cmp_eq_u32 s31, 12
	s_cselect_b32 s3, s20, s3
	s_cselect_b32 s2, s21, s2
	v_add_u32_e32 v158, s34, v165
	s_cselect_b32 s59, s23, s30
	s_cselect_b32 s58, s28, s29
	s_add_i32 s43, 0, 0x14000
	ds_read_b128 v[142:145], v158
	ds_read_b128 v[146:149], v158 offset:1024
	ds_read_b128 v[150:153], v158 offset:2048
	ds_read_b128 v[176:179], v158 offset:3072
	v_add_u32_e32 v158, s43, v165
	ds_read_b128 v[180:183], v158
	ds_read_b128 v[184:187], v158 offset:1024
	ds_read_b128 v[188:191], v158 offset:2048
	ds_read_b128 v[192:195], v158 offset:3072
	v_lshl_add_u64 v[158:159], s[56:57], 0, v[138:139]
	s_add_i32 m0, s11, 0xc000
	ds_read_b128 v[196:199], v175
	ds_read_b128 v[200:203], v175 offset:1024
	ds_read_b128 v[204:207], v175 offset:2048
	ds_read_b128 v[208:211], v175 offset:3072
	ds_read_b128 v[220:223], v175 offset:4096
	ds_read_b128 v[224:227], v175 offset:5120
	ds_read_b128 v[228:231], v175 offset:6144
	ds_read_b128 v[232:235], v175 offset:7168
	global_load_lds_dwordx4 v[158:159], off
	v_lshl_add_u64 v[158:159], s[56:57], 0, v[140:141]
	s_add_i32 m0, s11, 0xe000
	s_nop 0
	global_load_lds_dwordx4 v[158:159], off
	s_waitcnt vmcnt(8)
	s_waitcnt lgkmcnt(0)
	s_barrier
	s_setprio 3
	s_waitcnt lgkmcnt(0)
	v_mfma_f32_16x16x32_bf16 v[126:129], v[142:145], v[196:199], v[126:129]
	v_mfma_f32_16x16x32_bf16 v[118:121], v[150:153], v[196:199], v[118:121]
	v_mfma_f32_16x16x32_bf16 v[110:113], v[142:145], v[204:207], v[110:113]
	v_mfma_f32_16x16x32_bf16 v[102:105], v[150:153], v[204:207], v[102:105]
	v_mfma_f32_16x16x32_bf16 v[94:97], v[142:145], v[220:223], v[94:97]
	v_mfma_f32_16x16x32_bf16 v[86:89], v[150:153], v[220:223], v[86:89]
	v_mfma_f32_16x16x32_bf16 v[78:81], v[142:145], v[228:231], v[78:81]
	v_mfma_f32_16x16x32_bf16 v[70:73], v[150:153], v[228:231], v[70:73]
	v_mfma_f32_16x16x32_bf16 v[126:129], v[146:149], v[200:203], v[126:129]
	v_mfma_f32_16x16x32_bf16 v[118:121], v[176:179], v[200:203], v[118:121]
	v_mfma_f32_16x16x32_bf16 v[110:113], v[146:149], v[208:211], v[110:113]
	v_mfma_f32_16x16x32_bf16 v[102:105], v[176:179], v[208:211], v[102:105]
	v_mfma_f32_16x16x32_bf16 v[94:97], v[146:149], v[224:227], v[94:97]
	v_mfma_f32_16x16x32_bf16 v[86:89], v[176:179], v[224:227], v[86:89]
	v_mfma_f32_16x16x32_bf16 v[78:81], v[146:149], v[232:235], v[78:81]
	v_mfma_f32_16x16x32_bf16 v[70:73], v[176:179], v[232:235], v[70:73]
	s_setprio 0
	s_setprio 3
	v_mfma_f32_16x16x32_bf16 v[122:125], v[180:183], v[196:199], v[122:125]
	v_mfma_f32_16x16x32_bf16 v[114:117], v[188:191], v[196:199], v[114:117]
	v_mfma_f32_16x16x32_bf16 v[106:109], v[180:183], v[204:207], v[106:109]
	v_mfma_f32_16x16x32_bf16 v[98:101], v[188:191], v[204:207], v[98:101]
	v_mfma_f32_16x16x32_bf16 v[90:93], v[180:183], v[220:223], v[90:93]
	v_mfma_f32_16x16x32_bf16 v[82:85], v[188:191], v[220:223], v[82:85]
	v_mfma_f32_16x16x32_bf16 v[74:77], v[180:183], v[228:231], v[74:77]
	v_mfma_f32_16x16x32_bf16 v[66:69], v[188:191], v[228:231], v[66:69]
	v_mfma_f32_16x16x32_bf16 v[122:125], v[184:187], v[200:203], v[122:125]
	v_mfma_f32_16x16x32_bf16 v[114:117], v[192:195], v[200:203], v[114:117]
	v_mfma_f32_16x16x32_bf16 v[106:109], v[184:187], v[208:211], v[106:109]
	v_mfma_f32_16x16x32_bf16 v[98:101], v[192:195], v[208:211], v[98:101]
	v_mfma_f32_16x16x32_bf16 v[90:93], v[184:187], v[224:227], v[90:93]
	v_mfma_f32_16x16x32_bf16 v[82:85], v[192:195], v[224:227], v[82:85]
	v_mfma_f32_16x16x32_bf16 v[74:77], v[184:187], v[232:235], v[74:77]
	v_mfma_f32_16x16x32_bf16 v[66:69], v[192:195], v[232:235], v[66:69]
	s_setprio 0
	s_barrier
	s_add_i32 s34, s34, s8
	v_lshl_add_u64 v[158:159], s[58:59], 0, v[32:33]
	s_mov_b32 m0, s34
	ds_read_b128 v[196:199], v175 offset:16384
	ds_read_b128 v[200:203], v175 offset:17408
	ds_read_b128 v[204:207], v175 offset:18432
	ds_read_b128 v[208:211], v175 offset:19456
	ds_read_b128 v[220:223], v175 offset:20480
	ds_read_b128 v[224:227], v175 offset:21504
	ds_read_b128 v[228:231], v175 offset:22528
	ds_read_b128 v[232:235], v175 offset:23552
	global_load_lds_dwordx4 v[158:159], off
	s_add_i32 m0, s34, 0x2000
	s_add_u32 s34, s58, 0x40000
	v_lshl_add_u64 v[160:161], s[58:59], 0, v[130:131]
	s_addc_u32 s35, s59, 0
	s_add_i32 s43, s43, s8
	global_load_lds_dwordx4 v[160:161], off
	v_lshl_add_u64 v[162:163], s[34:35], 0, v[32:33]
	s_mov_b32 m0, s43
	v_lshl_add_u64 v[212:213], s[2:3], 0, v[132:133]
	global_load_lds_dwordx4 v[162:163], off
	v_lshl_add_u64 v[162:163], s[34:35], 0, v[130:131]
	s_add_i32 m0, s43, 0x2000
	s_nop 0
	global_load_lds_dwordx4 v[162:163], off
	v_lshl_add_u64 v[162:163], s[2:3], 0, v[134:135]
	s_mov_b32 m0, s11
	s_nop 0
	global_load_lds_dwordx4 v[162:163], off
	s_mov_b32 m0, s12
	s_nop 0
	global_load_lds_dwordx4 v[212:213], off
	s_waitcnt vmcnt(8)
	s_waitcnt lgkmcnt(0)
	s_barrier
	s_setprio 3
	s_waitcnt lgkmcnt(0)
	v_mfma_f32_16x16x32_bf16 v[62:65], v[142:145], v[196:199], v[62:65]
	v_mfma_f32_16x16x32_bf16 v[54:57], v[150:153], v[196:199], v[54:57]
	v_mfma_f32_16x16x32_bf16 v[46:49], v[142:145], v[204:207], v[46:49]
	v_mfma_f32_16x16x32_bf16 v[38:41], v[150:153], v[204:207], v[38:41]
	v_mfma_f32_16x16x32_bf16 v[28:31], v[142:145], v[220:223], v[28:31]
	v_mfma_f32_16x16x32_bf16 v[20:23], v[150:153], v[220:223], v[20:23]
	v_mfma_f32_16x16x32_bf16 v[12:15], v[142:145], v[228:231], v[12:15]
	v_mfma_f32_16x16x32_bf16 v[4:7], v[150:153], v[228:231], v[4:7]
	v_mfma_f32_16x16x32_bf16 v[62:65], v[146:149], v[200:203], v[62:65]
	v_mfma_f32_16x16x32_bf16 v[54:57], v[176:179], v[200:203], v[54:57]
	v_mfma_f32_16x16x32_bf16 v[46:49], v[146:149], v[208:211], v[46:49]
	v_mfma_f32_16x16x32_bf16 v[38:41], v[176:179], v[208:211], v[38:41]
	v_mfma_f32_16x16x32_bf16 v[28:31], v[146:149], v[224:227], v[28:31]
	v_mfma_f32_16x16x32_bf16 v[20:23], v[176:179], v[224:227], v[20:23]
	v_mfma_f32_16x16x32_bf16 v[12:15], v[146:149], v[232:235], v[12:15]
	v_mfma_f32_16x16x32_bf16 v[4:7], v[176:179], v[232:235], v[4:7]
	s_setprio 0
	s_setprio 3
	v_mfma_f32_16x16x32_bf16 v[58:61], v[180:183], v[196:199], v[58:61]
	v_mfma_f32_16x16x32_bf16 v[50:53], v[188:191], v[196:199], v[50:53]
	v_mfma_f32_16x16x32_bf16 v[42:45], v[180:183], v[204:207], v[42:45]
	v_mfma_f32_16x16x32_bf16 v[34:37], v[188:191], v[204:207], v[34:37]
	v_mfma_f32_16x16x32_bf16 v[24:27], v[180:183], v[220:223], v[24:27]
	v_mfma_f32_16x16x32_bf16 v[16:19], v[188:191], v[220:223], v[16:19]
	v_mfma_f32_16x16x32_bf16 v[8:11], v[180:183], v[228:231], v[8:11]
	v_mfma_f32_16x16x32_bf16 v[0:3], v[188:191], v[228:231], v[0:3]
	v_mfma_f32_16x16x32_bf16 v[58:61], v[184:187], v[200:203], v[58:61]
	v_mfma_f32_16x16x32_bf16 v[50:53], v[192:195], v[200:203], v[50:53]
	v_mfma_f32_16x16x32_bf16 v[42:45], v[184:187], v[208:211], v[42:45]
	v_mfma_f32_16x16x32_bf16 v[34:37], v[192:195], v[208:211], v[34:37]
	v_mfma_f32_16x16x32_bf16 v[24:27], v[184:187], v[224:227], v[24:27]
	v_mfma_f32_16x16x32_bf16 v[16:19], v[192:195], v[224:227], v[16:19]
	v_mfma_f32_16x16x32_bf16 v[8:11], v[184:187], v[232:235], v[8:11]
	v_mfma_f32_16x16x32_bf16 v[0:3], v[192:195], v[232:235], v[0:3]
	s_setprio 0
	s_barrier
	s_add_i32 s34, 0, 0x18000
	s_add_i32 s35, 0, 0x1c000
	v_add_u32_e32 v176, s34, v165
	v_add_u32_e32 v192, s35, v165
	ds_read_b128 v[142:145], v176
	ds_read_b128 v[146:149], v176 offset:1024
	ds_read_b128 v[150:153], v176 offset:2048
	ds_read_b128 v[176:179], v176 offset:3072
	ds_read_b128 v[180:183], v192
	ds_read_b128 v[184:187], v192 offset:1024
	ds_read_b128 v[188:191], v192 offset:2048
	ds_read_b128 v[192:195], v192 offset:3072
	s_add_u32 s2, s2, 0x40000
	s_addc_u32 s3, s3, 0
	s_mov_b32 m0, s13
	v_lshl_add_u64 v[236:237], s[2:3], 0, v[134:135]
	ds_read_b128 v[196:199], v175 offset:32768
	ds_read_b128 v[200:203], v175 offset:33792
	ds_read_b128 v[204:207], v175 offset:34816
	ds_read_b128 v[208:211], v175 offset:35840
	ds_read_b128 v[220:223], v175 offset:36864
	ds_read_b128 v[224:227], v175 offset:37888
	ds_read_b128 v[228:231], v175 offset:38912
	ds_read_b128 v[232:235], v175 offset:39936
	global_load_lds_dwordx4 v[236:237], off
	v_lshl_add_u64 v[236:237], s[2:3], 0, v[132:133]
	s_mov_b32 m0, s14
	s_nop 0
	global_load_lds_dwordx4 v[236:237], off
	s_waitcnt vmcnt(8)
	s_waitcnt lgkmcnt(0)
	s_barrier
	s_setprio 3
	s_waitcnt lgkmcnt(0)
	v_mfma_f32_16x16x32_bf16 v[126:129], v[142:145], v[196:199], v[126:129]
	v_mfma_f32_16x16x32_bf16 v[118:121], v[150:153], v[196:199], v[118:121]
	v_mfma_f32_16x16x32_bf16 v[110:113], v[142:145], v[204:207], v[110:113]
	v_mfma_f32_16x16x32_bf16 v[102:105], v[150:153], v[204:207], v[102:105]
	v_mfma_f32_16x16x32_bf16 v[94:97], v[142:145], v[220:223], v[94:97]
	v_mfma_f32_16x16x32_bf16 v[86:89], v[150:153], v[220:223], v[86:89]
	v_mfma_f32_16x16x32_bf16 v[78:81], v[142:145], v[228:231], v[78:81]
	v_mfma_f32_16x16x32_bf16 v[70:73], v[150:153], v[228:231], v[70:73]
	v_mfma_f32_16x16x32_bf16 v[126:129], v[146:149], v[200:203], v[126:129]
	v_mfma_f32_16x16x32_bf16 v[118:121], v[176:179], v[200:203], v[118:121]
	v_mfma_f32_16x16x32_bf16 v[110:113], v[146:149], v[208:211], v[110:113]
	v_mfma_f32_16x16x32_bf16 v[102:105], v[176:179], v[208:211], v[102:105]
	v_mfma_f32_16x16x32_bf16 v[94:97], v[146:149], v[224:227], v[94:97]
	v_mfma_f32_16x16x32_bf16 v[86:89], v[176:179], v[224:227], v[86:89]
	v_mfma_f32_16x16x32_bf16 v[78:81], v[146:149], v[232:235], v[78:81]
	v_mfma_f32_16x16x32_bf16 v[70:73], v[176:179], v[232:235], v[70:73]
	s_setprio 0
	s_setprio 3
	v_mfma_f32_16x16x32_bf16 v[122:125], v[180:183], v[196:199], v[122:125]
	v_mfma_f32_16x16x32_bf16 v[114:117], v[188:191], v[196:199], v[114:117]
	v_mfma_f32_16x16x32_bf16 v[106:109], v[180:183], v[204:207], v[106:109]
	v_mfma_f32_16x16x32_bf16 v[98:101], v[188:191], v[204:207], v[98:101]
	v_mfma_f32_16x16x32_bf16 v[90:93], v[180:183], v[220:223], v[90:93]
	v_mfma_f32_16x16x32_bf16 v[82:85], v[188:191], v[220:223], v[82:85]
	v_mfma_f32_16x16x32_bf16 v[74:77], v[180:183], v[228:231], v[74:77]
	v_mfma_f32_16x16x32_bf16 v[66:69], v[188:191], v[228:231], v[66:69]
	v_mfma_f32_16x16x32_bf16 v[122:125], v[184:187], v[200:203], v[122:125]
	v_mfma_f32_16x16x32_bf16 v[114:117], v[192:195], v[200:203], v[114:117]
	v_mfma_f32_16x16x32_bf16 v[106:109], v[184:187], v[208:211], v[106:109]
	v_mfma_f32_16x16x32_bf16 v[98:101], v[192:195], v[208:211], v[98:101]
	v_mfma_f32_16x16x32_bf16 v[90:93], v[184:187], v[224:227], v[90:93]
	v_mfma_f32_16x16x32_bf16 v[82:85], v[192:195], v[224:227], v[82:85]
	v_mfma_f32_16x16x32_bf16 v[74:77], v[184:187], v[232:235], v[74:77]
	v_mfma_f32_16x16x32_bf16 v[66:69], v[192:195], v[232:235], v[66:69]
	s_setprio 0
	s_barrier
	s_add_i32 s2, s34, s8
	v_lshl_add_u64 v[158:159], v[158:159], 0, s[24:25]
	s_mov_b32 m0, s2
	ds_read_b128 v[196:199], v175 offset:49152
	ds_read_b128 v[200:203], v175 offset:50176
	ds_read_b128 v[204:207], v175 offset:51200
	ds_read_b128 v[208:211], v175 offset:52224
	ds_read_b128 v[220:223], v175 offset:53248
	ds_read_b128 v[224:227], v175 offset:54272
	ds_read_b128 v[228:231], v175 offset:55296
	ds_read_b128 v[232:235], v175 offset:56320
	global_load_lds_dwordx4 v[158:159], off
	s_add_i32 m0, s2, 0x2000
	s_add_u32 s2, s58, 0x40080
	v_lshl_add_u64 v[158:159], v[160:161], 0, s[24:25]
	s_addc_u32 s3, s59, 0
	s_add_i32 s34, s35, s8
	global_load_lds_dwordx4 v[158:159], off
	v_lshl_add_u64 v[158:159], s[2:3], 0, v[32:33]
	s_mov_b32 m0, s34
	s_nop 0
	global_load_lds_dwordx4 v[158:159], off
	v_lshl_add_u64 v[158:159], s[2:3], 0, v[130:131]
	s_add_i32 m0, s34, 0x2000
	s_nop 0
	global_load_lds_dwordx4 v[158:159], off
	v_lshl_add_u64 v[158:159], v[162:163], 0, s[24:25]
	s_mov_b32 m0, s15
	s_nop 0
	global_load_lds_dwordx4 v[158:159], off
	v_lshl_add_u64 v[158:159], v[212:213], 0, s[24:25]
	s_mov_b32 m0, s17
	s_nop 0
	global_load_lds_dwordx4 v[158:159], off
	s_waitcnt vmcnt(8)
	s_waitcnt lgkmcnt(0)
	s_barrier
	s_setprio 3
	s_waitcnt lgkmcnt(0)
	v_mfma_f32_16x16x32_bf16 v[62:65], v[142:145], v[196:199], v[62:65]
	v_mfma_f32_16x16x32_bf16 v[54:57], v[150:153], v[196:199], v[54:57]
	v_mfma_f32_16x16x32_bf16 v[46:49], v[142:145], v[204:207], v[46:49]
	v_mfma_f32_16x16x32_bf16 v[38:41], v[150:153], v[204:207], v[38:41]
	v_mfma_f32_16x16x32_bf16 v[28:31], v[142:145], v[220:223], v[28:31]
	v_mfma_f32_16x16x32_bf16 v[20:23], v[150:153], v[220:223], v[20:23]
	v_mfma_f32_16x16x32_bf16 v[12:15], v[142:145], v[228:231], v[12:15]
	v_mfma_f32_16x16x32_bf16 v[4:7], v[150:153], v[228:231], v[4:7]
	v_mfma_f32_16x16x32_bf16 v[62:65], v[146:149], v[200:203], v[62:65]
	v_mfma_f32_16x16x32_bf16 v[54:57], v[176:179], v[200:203], v[54:57]
	v_mfma_f32_16x16x32_bf16 v[46:49], v[146:149], v[208:211], v[46:49]
	v_mfma_f32_16x16x32_bf16 v[38:41], v[176:179], v[208:211], v[38:41]
	v_mfma_f32_16x16x32_bf16 v[28:31], v[146:149], v[224:227], v[28:31]
	v_mfma_f32_16x16x32_bf16 v[20:23], v[176:179], v[224:227], v[20:23]
	v_mfma_f32_16x16x32_bf16 v[12:15], v[146:149], v[232:235], v[12:15]
	v_mfma_f32_16x16x32_bf16 v[4:7], v[176:179], v[232:235], v[4:7]
	s_setprio 0
	s_setprio 3
	v_mfma_f32_16x16x32_bf16 v[58:61], v[180:183], v[196:199], v[58:61]
	v_mfma_f32_16x16x32_bf16 v[50:53], v[188:191], v[196:199], v[50:53]
	v_mfma_f32_16x16x32_bf16 v[42:45], v[180:183], v[204:207], v[42:45]
	v_mfma_f32_16x16x32_bf16 v[34:37], v[188:191], v[204:207], v[34:37]
	v_mfma_f32_16x16x32_bf16 v[24:27], v[180:183], v[220:223], v[24:27]
	v_mfma_f32_16x16x32_bf16 v[16:19], v[188:191], v[220:223], v[16:19]
	v_mfma_f32_16x16x32_bf16 v[8:11], v[180:183], v[228:231], v[8:11]
	v_mfma_f32_16x16x32_bf16 v[0:3], v[188:191], v[228:231], v[0:3]
	v_mfma_f32_16x16x32_bf16 v[58:61], v[184:187], v[200:203], v[58:61]
	v_mfma_f32_16x16x32_bf16 v[50:53], v[192:195], v[200:203], v[50:53]
	v_mfma_f32_16x16x32_bf16 v[42:45], v[184:187], v[208:211], v[42:45]
	v_mfma_f32_16x16x32_bf16 v[34:37], v[192:195], v[208:211], v[34:37]
	v_mfma_f32_16x16x32_bf16 v[24:27], v[184:187], v[224:227], v[24:27]
	v_mfma_f32_16x16x32_bf16 v[16:19], v[192:195], v[224:227], v[16:19]
	v_mfma_f32_16x16x32_bf16 v[8:11], v[184:187], v[232:235], v[8:11]
	v_mfma_f32_16x16x32_bf16 v[0:3], v[192:195], v[232:235], v[0:3]
	s_setprio 0
	s_barrier
	s_add_i32 s31, s31, 2
	s_add_u32 s56, s56, 0x100
	s_addc_u32 s57, s57, 0
	s_add_u32 s29, s29, 0x100
	s_addc_u32 s30, s30, 0
	s_cmp_gt_u32 s31, 13
	s_cbranch_scc0 .LBB0_2557
	s_and_b64 vcc, exec, s[40:41]
	s_cbranch_vccz .LBB0_2560
	s_barrier

.LBB0_2574:
	s_add_u32 s2, s21, s6
	s_addc_u32 s3, s23, s7
	s_add_u32 s2, s2, 0x9d00100
	s_addc_u32 s3, s3, 0
	s_add_u32 s31, s28, s6
	s_addc_u32 s35, s29, s7
	s_add_i32 s37, 0, 0x10000
	s_cmpk_eq_i32 s6, 0x700
	s_cselect_b32 s43, s41, s3
	s_cselect_b32 s42, s40, s2
	v_add_u32_e32 v81, s37, v79
	s_cselect_b32 s3, s39, s35
	s_cselect_b32 s2, s38, s31
	s_add_i32 s31, 0, 0x14000
	ds_read_b128 v[82:85], v81
	ds_read_b128 v[86:89], v81 offset:1024
	ds_read_b128 v[90:93], v81 offset:2048
	ds_read_b128 v[94:97], v81 offset:3072
	v_add_u32_e32 v81, s31, v79
	ds_read_b128 v[98:101], v81
	ds_read_b128 v[102:105], v81 offset:1024
	ds_read_b128 v[106:109], v81 offset:2048
	ds_read_b128 v[110:113], v81 offset:3072
	v_lshl_add_u64 v[146:147], v[72:73], 0, s[6:7]
	s_add_i32 m0, s13, 0xc000
	ds_read_b128 v[114:117], v80
	ds_read_b128 v[118:121], v80 offset:1024
	ds_read_b128 v[122:125], v80 offset:2048
	ds_read_b128 v[126:129], v80 offset:3072
	ds_read_b128 v[130:133], v80 offset:4096
	ds_read_b128 v[134:137], v80 offset:5120
	ds_read_b128 v[138:141], v80 offset:6144
	ds_read_b128 v[142:145], v80 offset:7168
	global_load_lds_dwordx4 v[146:147], off
	v_lshl_add_u64 v[146:147], v[74:75], 0, s[6:7]
	s_add_i32 m0, s13, 0xe000
	s_nop 0
	global_load_lds_dwordx4 v[146:147], off
	s_waitcnt vmcnt(8)
	s_waitcnt lgkmcnt(0)
	s_barrier
	s_setprio 3
	s_waitcnt lgkmcnt(0)
	v_mfma_f32_16x16x32_bf16 v[62:65], v[82:85], v[114:117], v[62:65]
	v_mfma_f32_16x16x32_bf16 v[54:57], v[90:93], v[114:117], v[54:57]
	v_mfma_f32_16x16x32_bf16 v[46:49], v[82:85], v[122:125], v[46:49]
	v_mfma_f32_16x16x32_bf16 v[38:41], v[90:93], v[122:125], v[38:41]
	v_mfma_f32_16x16x32_bf16 v[28:31], v[82:85], v[130:133], v[28:31]
	v_mfma_f32_16x16x32_bf16 v[20:23], v[90:93], v[130:133], v[20:23]
	v_mfma_f32_16x16x32_bf16 v[12:15], v[82:85], v[138:141], v[12:15]
	v_mfma_f32_16x16x32_bf16 v[4:7], v[90:93], v[138:141], v[4:7]
	v_mfma_f32_16x16x32_bf16 v[62:65], v[86:89], v[118:121], v[62:65]
	v_mfma_f32_16x16x32_bf16 v[54:57], v[94:97], v[118:121], v[54:57]
	v_mfma_f32_16x16x32_bf16 v[46:49], v[86:89], v[126:129], v[46:49]
	v_mfma_f32_16x16x32_bf16 v[38:41], v[94:97], v[126:129], v[38:41]
	v_mfma_f32_16x16x32_bf16 v[28:31], v[86:89], v[134:137], v[28:31]
	v_mfma_f32_16x16x32_bf16 v[20:23], v[94:97], v[134:137], v[20:23]
	v_mfma_f32_16x16x32_bf16 v[12:15], v[86:89], v[142:145], v[12:15]
	v_mfma_f32_16x16x32_bf16 v[4:7], v[94:97], v[142:145], v[4:7]
	s_setprio 0
	s_setprio 3
	v_mfma_f32_16x16x32_bf16 v[58:61], v[98:101], v[114:117], v[58:61]
	v_mfma_f32_16x16x32_bf16 v[50:53], v[106:109], v[114:117], v[50:53]
	v_mfma_f32_16x16x32_bf16 v[42:45], v[98:101], v[122:125], v[42:45]
	v_mfma_f32_16x16x32_bf16 v[34:37], v[106:109], v[122:125], v[34:37]
	v_mfma_f32_16x16x32_bf16 v[24:27], v[98:101], v[130:133], v[24:27]
	v_mfma_f32_16x16x32_bf16 v[16:19], v[106:109], v[130:133], v[16:19]
	v_mfma_f32_16x16x32_bf16 v[8:11], v[98:101], v[138:141], v[8:11]
	v_mfma_f32_16x16x32_bf16 v[0:3], v[106:109], v[138:141], v[0:3]
	v_mfma_f32_16x16x32_bf16 v[58:61], v[102:105], v[118:121], v[58:61]
	v_mfma_f32_16x16x32_bf16 v[50:53], v[110:113], v[118:121], v[50:53]
	v_mfma_f32_16x16x32_bf16 v[42:45], v[102:105], v[126:129], v[42:45]
	v_mfma_f32_16x16x32_bf16 v[34:37], v[110:113], v[126:129], v[34:37]
	v_mfma_f32_16x16x32_bf16 v[24:27], v[102:105], v[134:137], v[24:27]
	v_mfma_f32_16x16x32_bf16 v[16:19], v[110:113], v[134:137], v[16:19]
	v_mfma_f32_16x16x32_bf16 v[8:11], v[102:105], v[142:145], v[8:11]
	v_mfma_f32_16x16x32_bf16 v[0:3], v[110:113], v[142:145], v[0:3]
	s_setprio 0
	s_barrier
	s_add_i32 s35, s37, s12
	v_lshl_add_u64 v[146:147], s[2:3], 0, v[32:33]
	s_mov_b32 m0, s35
	v_lshl_add_u64 v[148:149], s[2:3], 0, v[66:67]
	global_load_lds_dwordx4 v[146:147], off
	s_add_i32 m0, s35, 0x2000
	s_add_u32 s44, s2, 0x40000
	s_addc_u32 s45, s3, 0
	s_add_i32 s31, s31, s12
	global_load_lds_dwordx4 v[148:149], off
	v_lshl_add_u64 v[82:83], s[44:45], 0, v[32:33]
	s_mov_b32 m0, s31
	v_lshl_add_u64 v[150:151], s[42:43], 0, v[70:71]
	global_load_lds_dwordx4 v[82:83], off
	v_lshl_add_u64 v[82:83], s[44:45], 0, v[66:67]
	s_add_i32 m0, s31, 0x2000
	v_lshl_add_u64 v[152:153], s[42:43], 0, v[68:69]
	global_load_lds_dwordx4 v[82:83], off
	s_mov_b32 m0, s13
	s_nop 0
	global_load_lds_dwordx4 v[150:151], off
	s_mov_b32 m0, s14
	s_nop 0
	global_load_lds_dwordx4 v[152:153], off
	s_waitcnt vmcnt(8)
	s_waitcnt lgkmcnt(0)
	s_barrier
	s_barrier
	s_add_i32 s31, 0, 0x18000
	v_add_u32_e32 v81, s31, v79
	s_add_i32 s35, 0, 0x1c000
	ds_read_b128 v[82:85], v81
	ds_read_b128 v[86:89], v81 offset:1024
	ds_read_b128 v[90:93], v81 offset:2048
	ds_read_b128 v[94:97], v81 offset:3072
	v_add_u32_e32 v81, s35, v79
	ds_read_b128 v[98:101], v81
	ds_read_b128 v[102:105], v81 offset:1024
	ds_read_b128 v[106:109], v81 offset:2048
	ds_read_b128 v[110:113], v81 offset:3072
	s_add_u32 s42, s42, 0x40000
	s_addc_u32 s43, s43, 0
	s_mov_b32 m0, s15
	v_lshl_add_u64 v[158:159], s[42:43], 0, v[70:71]
	ds_read_b128 v[114:117], v80 offset:32768
	ds_read_b128 v[118:121], v80 offset:33792
	ds_read_b128 v[122:125], v80 offset:34816
	ds_read_b128 v[126:129], v80 offset:35840
	ds_read_b128 v[130:133], v80 offset:36864
	ds_read_b128 v[134:137], v80 offset:37888
	ds_read_b128 v[138:141], v80 offset:38912
	ds_read_b128 v[142:145], v80 offset:39936
	global_load_lds_dwordx4 v[158:159], off
	v_lshl_add_u64 v[158:159], s[42:43], 0, v[68:69]
	s_mov_b32 m0, s17
	s_nop 0
	global_load_lds_dwordx4 v[158:159], off
	s_waitcnt vmcnt(8)
	s_waitcnt lgkmcnt(0)
	s_barrier
	s_setprio 3
	s_waitcnt lgkmcnt(0)
	v_mfma_f32_16x16x32_bf16 v[62:65], v[82:85], v[114:117], v[62:65]
	v_mfma_f32_16x16x32_bf16 v[54:57], v[90:93], v[114:117], v[54:57]
	v_mfma_f32_16x16x32_bf16 v[46:49], v[82:85], v[122:125], v[46:49]
	v_mfma_f32_16x16x32_bf16 v[38:41], v[90:93], v[122:125], v[38:41]
	v_mfma_f32_16x16x32_bf16 v[28:31], v[82:85], v[130:133], v[28:31]
	v_mfma_f32_16x16x32_bf16 v[20:23], v[90:93], v[130:133], v[20:23]
	v_mfma_f32_16x16x32_bf16 v[12:15], v[82:85], v[138:141], v[12:15]
	v_mfma_f32_16x16x32_bf16 v[4:7], v[90:93], v[138:141], v[4:7]
	v_mfma_f32_16x16x32_bf16 v[62:65], v[86:89], v[118:121], v[62:65]
	v_mfma_f32_16x16x32_bf16 v[54:57], v[94:97], v[118:121], v[54:57]
	v_mfma_f32_16x16x32_bf16 v[46:49], v[86:89], v[126:129], v[46:49]
	v_mfma_f32_16x16x32_bf16 v[38:41], v[94:97], v[126:129], v[38:41]
	v_mfma_f32_16x16x32_bf16 v[28:31], v[86:89], v[134:137], v[28:31]
	v_mfma_f32_16x16x32_bf16 v[20:23], v[94:97], v[134:137], v[20:23]
	v_mfma_f32_16x16x32_bf16 v[12:15], v[86:89], v[142:145], v[12:15]
	v_mfma_f32_16x16x32_bf16 v[4:7], v[94:97], v[142:145], v[4:7]
	s_setprio 0
	s_setprio 3
	v_mfma_f32_16x16x32_bf16 v[58:61], v[98:101], v[114:117], v[58:61]
	v_mfma_f32_16x16x32_bf16 v[50:53], v[106:109], v[114:117], v[50:53]
	v_mfma_f32_16x16x32_bf16 v[42:45], v[98:101], v[122:125], v[42:45]
	v_mfma_f32_16x16x32_bf16 v[34:37], v[106:109], v[122:125], v[34:37]
	v_mfma_f32_16x16x32_bf16 v[24:27], v[98:101], v[130:133], v[24:27]
	v_mfma_f32_16x16x32_bf16 v[16:19], v[106:109], v[130:133], v[16:19]
	v_mfma_f32_16x16x32_bf16 v[8:11], v[98:101], v[138:141], v[8:11]
	v_mfma_f32_16x16x32_bf16 v[0:3], v[106:109], v[138:141], v[0:3]
	v_mfma_f32_16x16x32_bf16 v[58:61], v[102:105], v[118:121], v[58:61]
	v_mfma_f32_16x16x32_bf16 v[50:53], v[110:113], v[118:121], v[50:53]
	v_mfma_f32_16x16x32_bf16 v[42:45], v[102:105], v[126:129], v[42:45]
	v_mfma_f32_16x16x32_bf16 v[34:37], v[110:113], v[126:129], v[34:37]
	v_mfma_f32_16x16x32_bf16 v[24:27], v[102:105], v[134:137], v[24:27]
	v_mfma_f32_16x16x32_bf16 v[16:19], v[110:113], v[134:137], v[16:19]
	v_mfma_f32_16x16x32_bf16 v[8:11], v[102:105], v[142:145], v[8:11]
	v_mfma_f32_16x16x32_bf16 v[0:3], v[110:113], v[142:145], v[0:3]
	s_setprio 0
	s_barrier
	s_add_i32 s31, s31, s12
	v_lshl_add_u64 v[82:83], v[146:147], 0, s[24:25]
	s_mov_b32 m0, s31
	s_nop 0
	global_load_lds_dwordx4 v[82:83], off
	s_add_i32 m0, s31, 0x2000
	s_add_u32 s2, s2, 0x40080
	v_lshl_add_u64 v[82:83], v[148:149], 0, s[24:25]
	s_addc_u32 s3, s3, 0
	s_add_i32 s31, s35, s12
	global_load_lds_dwordx4 v[82:83], off
	v_lshl_add_u64 v[82:83], s[2:3], 0, v[32:33]
	s_mov_b32 m0, s31
	s_nop 0
	global_load_lds_dwordx4 v[82:83], off
	v_lshl_add_u64 v[82:83], s[2:3], 0, v[66:67]
	s_add_i32 m0, s31, 0x2000
	s_nop 0
	global_load_lds_dwordx4 v[82:83], off
	v_lshl_add_u64 v[82:83], v[150:151], 0, s[24:25]
	s_mov_b32 m0, s19
	s_nop 0
	global_load_lds_dwordx4 v[82:83], off
	v_lshl_add_u64 v[82:83], v[152:153], 0, s[24:25]
	s_mov_b32 m0, s20
	s_nop 0
	global_load_lds_dwordx4 v[82:83], off
	s_waitcnt vmcnt(8)
	s_waitcnt lgkmcnt(0)
	s_barrier
	s_barrier
	s_add_i32 s30, s30, 2
	s_add_u32 s6, s6, 0x100
	s_addc_u32 s7, s7, 0
	s_cmp_gt_u32 s30, 13
	s_cbranch_scc0 .LBB0_2574
	s_cmpk_lt_u32 s8, 0x100
	s_cbranch_scc0 .LBB0_2577
	s_barrier

.LBB0_2858:
	s_add_u32 s56, s58, 0x100
	s_addc_u32 s57, s59, 0
	s_add_i32 s63, 0, 0x10000
	s_cmp_eq_u32 s62, 40
	s_cselect_b32 s3, s43, s57
	s_cselect_b32 s2, s42, s56
	s_cselect_b32 s61, s55, s29
	s_cselect_b32 s60, s54, s28
	s_add_i32 s64, 0, 0x14000
	v_add_u32_e32 v142, s63, v210
	v_add_u32_e32 v158, s64, v210
	ds_read_b128 v[114:117], v142
	ds_read_b128 v[122:125], v142 offset:1024
	ds_read_b128 v[130:133], v142 offset:2048
	ds_read_b128 v[142:145], v142 offset:3072
	ds_read_b128 v[146:149], v158
	ds_read_b128 v[150:153], v158 offset:1024
	ds_read_b128 v[182:185], v158 offset:2048
	ds_read_b128 v[186:189], v158 offset:3072
	v_lshl_add_u64 v[158:159], s[58:59], 0, v[178:179]
	s_add_i32 m0, s30, 0xc000
	ds_read_b128 v[190:193], v32
	ds_read_b128 v[194:197], v32 offset:1024
	ds_read_b128 v[220:223], v32 offset:2048
	ds_read_b128 v[224:227], v32 offset:3072
	ds_read_b128 v[228:231], v32 offset:4096
	ds_read_b128 v[232:235], v32 offset:5120
	ds_read_b128 v[236:239], v32 offset:6144
	ds_read_b128 v[240:243], v32 offset:7168
	global_load_lds_dwordx4 v[158:159], off
	v_lshl_add_u64 v[158:159], s[58:59], 0, v[180:181]
	s_add_i32 m0, s30, 0xe000
	s_nop 0
	global_load_lds_dwordx4 v[158:159], off
	s_waitcnt vmcnt(8)
	s_waitcnt lgkmcnt(0)
	s_barrier
	s_setprio 3
	s_waitcnt lgkmcnt(0)
	v_mfma_f32_16x16x32_bf16 v[138:141], v[114:117], v[190:193], v[138:141]
	v_mfma_f32_16x16x32_bf16 v[134:137], v[130:133], v[190:193], v[134:137]
	v_mfma_f32_16x16x32_bf16 v[110:113], v[114:117], v[220:223], v[110:113]
	v_mfma_f32_16x16x32_bf16 v[106:109], v[130:133], v[220:223], v[106:109]
	v_mfma_f32_16x16x32_bf16 v[94:97], v[114:117], v[228:231], v[94:97]
	v_mfma_f32_16x16x32_bf16 v[90:93], v[130:133], v[228:231], v[90:93]
	v_mfma_f32_16x16x32_bf16 v[78:81], v[114:117], v[236:239], v[78:81]
	v_mfma_f32_16x16x32_bf16 v[74:77], v[130:133], v[236:239], v[74:77]
	v_mfma_f32_16x16x32_bf16 v[138:141], v[122:125], v[194:197], v[138:141]
	v_mfma_f32_16x16x32_bf16 v[134:137], v[142:145], v[194:197], v[134:137]
	v_mfma_f32_16x16x32_bf16 v[110:113], v[122:125], v[224:227], v[110:113]
	v_mfma_f32_16x16x32_bf16 v[106:109], v[142:145], v[224:227], v[106:109]
	v_mfma_f32_16x16x32_bf16 v[94:97], v[122:125], v[232:235], v[94:97]
	v_mfma_f32_16x16x32_bf16 v[90:93], v[142:145], v[232:235], v[90:93]
	v_mfma_f32_16x16x32_bf16 v[78:81], v[122:125], v[240:243], v[78:81]
	v_mfma_f32_16x16x32_bf16 v[74:77], v[142:145], v[240:243], v[74:77]
	s_setprio 0
	s_setprio 3
	v_mfma_f32_16x16x32_bf16 v[126:129], v[146:149], v[190:193], v[126:129]
	v_mfma_f32_16x16x32_bf16 v[118:121], v[182:185], v[190:193], v[118:121]
	v_mfma_f32_16x16x32_bf16 v[102:105], v[146:149], v[220:223], v[102:105]
	v_mfma_f32_16x16x32_bf16 v[98:101], v[182:185], v[220:223], v[98:101]
	v_mfma_f32_16x16x32_bf16 v[86:89], v[146:149], v[228:231], v[86:89]
	v_mfma_f32_16x16x32_bf16 v[82:85], v[182:185], v[228:231], v[82:85]
	v_mfma_f32_16x16x32_bf16 v[70:73], v[146:149], v[236:239], v[70:73]
	v_mfma_f32_16x16x32_bf16 v[66:69], v[182:185], v[236:239], v[66:69]
	v_mfma_f32_16x16x32_bf16 v[126:129], v[150:153], v[194:197], v[126:129]
	v_mfma_f32_16x16x32_bf16 v[118:121], v[186:189], v[194:197], v[118:121]
	v_mfma_f32_16x16x32_bf16 v[102:105], v[150:153], v[224:227], v[102:105]
	v_mfma_f32_16x16x32_bf16 v[98:101], v[186:189], v[224:227], v[98:101]
	v_mfma_f32_16x16x32_bf16 v[86:89], v[150:153], v[232:235], v[86:89]
	v_mfma_f32_16x16x32_bf16 v[82:85], v[186:189], v[232:235], v[82:85]
	v_mfma_f32_16x16x32_bf16 v[70:73], v[150:153], v[240:243], v[70:73]
	v_mfma_f32_16x16x32_bf16 v[66:69], v[186:189], v[240:243], v[66:69]
	s_setprio 0
	s_barrier
	s_add_i32 s58, s63, s17
	v_lshl_add_u64 v[158:159], s[60:61], 0, v[174:175]
	s_mov_b32 m0, s58
	ds_read_b128 v[190:193], v32 offset:16384
	ds_read_b128 v[194:197], v32 offset:17408
	ds_read_b128 v[220:223], v32 offset:18432
	ds_read_b128 v[224:227], v32 offset:19456
	ds_read_b128 v[228:231], v32 offset:20480
	ds_read_b128 v[232:235], v32 offset:21504
	ds_read_b128 v[236:239], v32 offset:22528
	ds_read_b128 v[240:243], v32 offset:23552
	global_load_lds_dwordx4 v[158:159], off
	s_add_i32 m0, s58, 0x2000
	s_add_u32 s58, s60, 0xb0000
	v_lshl_add_u64 v[160:161], s[60:61], 0, v[170:171]
	s_addc_u32 s59, s61, 0
	s_add_i32 s63, s64, s17
	global_load_lds_dwordx4 v[160:161], off
	v_lshl_add_u64 v[198:199], s[58:59], 0, v[174:175]
	s_mov_b32 m0, s63
	v_lshl_add_u64 v[212:213], s[2:3], 0, v[172:173]
	global_load_lds_dwordx4 v[198:199], off
	v_lshl_add_u64 v[198:199], s[58:59], 0, v[170:171]
	s_add_i32 m0, s63, 0x2000
	s_nop 0
	global_load_lds_dwordx4 v[198:199], off
	v_lshl_add_u64 v[198:199], s[2:3], 0, v[176:177]
	s_mov_b32 m0, s30
	s_nop 0
	global_load_lds_dwordx4 v[198:199], off
	s_mov_b32 m0, s31
	s_nop 0
	global_load_lds_dwordx4 v[212:213], off
	s_waitcnt vmcnt(8)
	s_waitcnt lgkmcnt(0)
	s_barrier
	s_setprio 3
	s_waitcnt lgkmcnt(0)
	v_mfma_f32_16x16x32_bf16 v[62:65], v[114:117], v[190:193], v[62:65]
	v_mfma_f32_16x16x32_bf16 v[58:61], v[130:133], v[190:193], v[58:61]
	v_mfma_f32_16x16x32_bf16 v[46:49], v[114:117], v[220:223], v[46:49]
	v_mfma_f32_16x16x32_bf16 v[42:45], v[130:133], v[220:223], v[42:45]
	v_mfma_f32_16x16x32_bf16 v[28:31], v[114:117], v[228:231], v[28:31]
	v_mfma_f32_16x16x32_bf16 v[24:27], v[130:133], v[228:231], v[24:27]
	v_mfma_f32_16x16x32_bf16 v[12:15], v[114:117], v[236:239], v[12:15]
	v_mfma_f32_16x16x32_bf16 v[8:11], v[130:133], v[236:239], v[8:11]
	v_mfma_f32_16x16x32_bf16 v[62:65], v[122:125], v[194:197], v[62:65]
	v_mfma_f32_16x16x32_bf16 v[58:61], v[142:145], v[194:197], v[58:61]
	v_mfma_f32_16x16x32_bf16 v[46:49], v[122:125], v[224:227], v[46:49]
	v_mfma_f32_16x16x32_bf16 v[42:45], v[142:145], v[224:227], v[42:45]
	v_mfma_f32_16x16x32_bf16 v[28:31], v[122:125], v[232:235], v[28:31]
	v_mfma_f32_16x16x32_bf16 v[24:27], v[142:145], v[232:235], v[24:27]
	v_mfma_f32_16x16x32_bf16 v[12:15], v[122:125], v[240:243], v[12:15]
	v_mfma_f32_16x16x32_bf16 v[8:11], v[142:145], v[240:243], v[8:11]
	s_setprio 0
	s_setprio 3
	v_mfma_f32_16x16x32_bf16 v[54:57], v[146:149], v[190:193], v[54:57]
	v_mfma_f32_16x16x32_bf16 v[50:53], v[182:185], v[190:193], v[50:53]
	v_mfma_f32_16x16x32_bf16 v[38:41], v[146:149], v[220:223], v[38:41]
	v_mfma_f32_16x16x32_bf16 v[34:37], v[182:185], v[220:223], v[34:37]
	v_mfma_f32_16x16x32_bf16 v[20:23], v[146:149], v[228:231], v[20:23]
	v_mfma_f32_16x16x32_bf16 v[16:19], v[182:185], v[228:231], v[16:19]
	v_mfma_f32_16x16x32_bf16 v[4:7], v[146:149], v[236:239], v[4:7]
	v_mfma_f32_16x16x32_bf16 v[0:3], v[182:185], v[236:239], v[0:3]
	v_mfma_f32_16x16x32_bf16 v[54:57], v[150:153], v[194:197], v[54:57]
	v_mfma_f32_16x16x32_bf16 v[50:53], v[186:189], v[194:197], v[50:53]
	v_mfma_f32_16x16x32_bf16 v[38:41], v[150:153], v[224:227], v[38:41]
	v_mfma_f32_16x16x32_bf16 v[34:37], v[186:189], v[224:227], v[34:37]
	v_mfma_f32_16x16x32_bf16 v[20:23], v[150:153], v[232:235], v[20:23]
	v_mfma_f32_16x16x32_bf16 v[16:19], v[186:189], v[232:235], v[16:19]
	v_mfma_f32_16x16x32_bf16 v[4:7], v[150:153], v[240:243], v[4:7]
	v_mfma_f32_16x16x32_bf16 v[0:3], v[186:189], v[240:243], v[0:3]
	s_setprio 0
	s_barrier
	s_add_i32 s58, 0, 0x18000
	s_add_i32 s59, 0, 0x1c000
	v_add_u32_e32 v142, s58, v210
	v_add_u32_e32 v186, s59, v210
	ds_read_b128 v[114:117], v142
	ds_read_b128 v[122:125], v142 offset:1024
	ds_read_b128 v[130:133], v142 offset:2048
	ds_read_b128 v[142:145], v142 offset:3072
	ds_read_b128 v[146:149], v186
	ds_read_b128 v[150:153], v186 offset:1024
	ds_read_b128 v[182:185], v186 offset:2048
	ds_read_b128 v[186:189], v186 offset:3072
	s_add_u32 s2, s2, 0xb0000
	s_addc_u32 s3, s3, 0
	s_mov_b32 m0, s79
	v_lshl_add_u64 v[244:245], s[2:3], 0, v[176:177]
	ds_read_b128 v[190:193], v32 offset:32768
	ds_read_b128 v[194:197], v32 offset:33792
	ds_read_b128 v[220:223], v32 offset:34816
	ds_read_b128 v[224:227], v32 offset:35840
	ds_read_b128 v[228:231], v32 offset:36864
	ds_read_b128 v[232:235], v32 offset:37888
	ds_read_b128 v[236:239], v32 offset:38912
	ds_read_b128 v[240:243], v32 offset:39936
	global_load_lds_dwordx4 v[244:245], off
	v_lshl_add_u64 v[244:245], s[2:3], 0, v[172:173]
	s_mov_b32 m0, s80
	s_nop 0
	global_load_lds_dwordx4 v[244:245], off
	s_waitcnt vmcnt(8)
	s_waitcnt lgkmcnt(0)
	s_barrier
	s_setprio 3
	s_waitcnt lgkmcnt(0)
	v_mfma_f32_16x16x32_bf16 v[138:141], v[114:117], v[190:193], v[138:141]
	v_mfma_f32_16x16x32_bf16 v[134:137], v[130:133], v[190:193], v[134:137]
	v_mfma_f32_16x16x32_bf16 v[110:113], v[114:117], v[220:223], v[110:113]
	v_mfma_f32_16x16x32_bf16 v[106:109], v[130:133], v[220:223], v[106:109]
	v_mfma_f32_16x16x32_bf16 v[94:97], v[114:117], v[228:231], v[94:97]
	v_mfma_f32_16x16x32_bf16 v[90:93], v[130:133], v[228:231], v[90:93]
	v_mfma_f32_16x16x32_bf16 v[78:81], v[114:117], v[236:239], v[78:81]
	v_mfma_f32_16x16x32_bf16 v[74:77], v[130:133], v[236:239], v[74:77]
	v_mfma_f32_16x16x32_bf16 v[138:141], v[122:125], v[194:197], v[138:141]
	v_mfma_f32_16x16x32_bf16 v[134:137], v[142:145], v[194:197], v[134:137]
	v_mfma_f32_16x16x32_bf16 v[110:113], v[122:125], v[224:227], v[110:113]
	v_mfma_f32_16x16x32_bf16 v[106:109], v[142:145], v[224:227], v[106:109]
	v_mfma_f32_16x16x32_bf16 v[94:97], v[122:125], v[232:235], v[94:97]
	v_mfma_f32_16x16x32_bf16 v[90:93], v[142:145], v[232:235], v[90:93]
	v_mfma_f32_16x16x32_bf16 v[78:81], v[122:125], v[240:243], v[78:81]
	v_mfma_f32_16x16x32_bf16 v[74:77], v[142:145], v[240:243], v[74:77]
	s_setprio 0
	s_setprio 3
	v_mfma_f32_16x16x32_bf16 v[126:129], v[146:149], v[190:193], v[126:129]
	v_mfma_f32_16x16x32_bf16 v[118:121], v[182:185], v[190:193], v[118:121]
	v_mfma_f32_16x16x32_bf16 v[102:105], v[146:149], v[220:223], v[102:105]
	v_mfma_f32_16x16x32_bf16 v[98:101], v[182:185], v[220:223], v[98:101]
	v_mfma_f32_16x16x32_bf16 v[86:89], v[146:149], v[228:231], v[86:89]
	v_mfma_f32_16x16x32_bf16 v[82:85], v[182:185], v[228:231], v[82:85]
	v_mfma_f32_16x16x32_bf16 v[70:73], v[146:149], v[236:239], v[70:73]
	v_mfma_f32_16x16x32_bf16 v[66:69], v[182:185], v[236:239], v[66:69]
	v_mfma_f32_16x16x32_bf16 v[126:129], v[150:153], v[194:197], v[126:129]
	v_mfma_f32_16x16x32_bf16 v[118:121], v[186:189], v[194:197], v[118:121]
	v_mfma_f32_16x16x32_bf16 v[102:105], v[150:153], v[224:227], v[102:105]
	v_mfma_f32_16x16x32_bf16 v[98:101], v[186:189], v[224:227], v[98:101]
	v_mfma_f32_16x16x32_bf16 v[86:89], v[150:153], v[232:235], v[86:89]
	v_mfma_f32_16x16x32_bf16 v[82:85], v[186:189], v[232:235], v[82:85]
	v_mfma_f32_16x16x32_bf16 v[70:73], v[150:153], v[240:243], v[70:73]
	v_mfma_f32_16x16x32_bf16 v[66:69], v[186:189], v[240:243], v[66:69]
	s_setprio 0
	s_barrier
	s_add_i32 s2, s58, s17
	v_lshl_add_u64 v[158:159], v[158:159], 0, s[24:25]
	s_mov_b32 m0, s2
	ds_read_b128 v[190:193], v32 offset:49152
	ds_read_b128 v[194:197], v32 offset:50176
	ds_read_b128 v[220:223], v32 offset:51200
	ds_read_b128 v[224:227], v32 offset:52224
	ds_read_b128 v[228:231], v32 offset:53248
	ds_read_b128 v[232:235], v32 offset:54272
	ds_read_b128 v[236:239], v32 offset:55296
	ds_read_b128 v[240:243], v32 offset:56320
	global_load_lds_dwordx4 v[158:159], off
	s_add_i32 m0, s2, 0x2000
	s_add_u32 s2, s60, 0xb0080
	v_lshl_add_u64 v[158:159], v[160:161], 0, s[24:25]
	s_addc_u32 s3, s61, 0
	s_add_i32 s58, s59, s17
	global_load_lds_dwordx4 v[158:159], off
	v_lshl_add_u64 v[158:159], s[2:3], 0, v[174:175]
	s_mov_b32 m0, s58
	s_nop 0
	global_load_lds_dwordx4 v[158:159], off
	v_lshl_add_u64 v[158:159], s[2:3], 0, v[170:171]
	s_add_i32 m0, s58, 0x2000
	s_nop 0
	global_load_lds_dwordx4 v[158:159], off
	v_lshl_add_u64 v[158:159], v[198:199], 0, s[24:25]
	s_mov_b32 m0, s8
	s_nop 0
	global_load_lds_dwordx4 v[158:159], off
	v_lshl_add_u64 v[158:159], v[212:213], 0, s[24:25]
	s_mov_b32 m0, s11
	s_nop 0
	global_load_lds_dwordx4 v[158:159], off
	s_waitcnt vmcnt(8)
	s_waitcnt lgkmcnt(0)
	s_barrier
	s_setprio 3
	s_waitcnt lgkmcnt(0)
	v_mfma_f32_16x16x32_bf16 v[62:65], v[114:117], v[190:193], v[62:65]
	v_mfma_f32_16x16x32_bf16 v[58:61], v[130:133], v[190:193], v[58:61]
	v_mfma_f32_16x16x32_bf16 v[46:49], v[114:117], v[220:223], v[46:49]
	v_mfma_f32_16x16x32_bf16 v[42:45], v[130:133], v[220:223], v[42:45]
	v_mfma_f32_16x16x32_bf16 v[28:31], v[114:117], v[228:231], v[28:31]
	v_mfma_f32_16x16x32_bf16 v[24:27], v[130:133], v[228:231], v[24:27]
	v_mfma_f32_16x16x32_bf16 v[12:15], v[114:117], v[236:239], v[12:15]
	v_mfma_f32_16x16x32_bf16 v[8:11], v[130:133], v[236:239], v[8:11]
	v_mfma_f32_16x16x32_bf16 v[62:65], v[122:125], v[194:197], v[62:65]
	v_mfma_f32_16x16x32_bf16 v[58:61], v[142:145], v[194:197], v[58:61]
	v_mfma_f32_16x16x32_bf16 v[46:49], v[122:125], v[224:227], v[46:49]
	v_mfma_f32_16x16x32_bf16 v[42:45], v[142:145], v[224:227], v[42:45]
	v_mfma_f32_16x16x32_bf16 v[28:31], v[122:125], v[232:235], v[28:31]
	v_mfma_f32_16x16x32_bf16 v[24:27], v[142:145], v[232:235], v[24:27]
	v_mfma_f32_16x16x32_bf16 v[12:15], v[122:125], v[240:243], v[12:15]
	v_mfma_f32_16x16x32_bf16 v[8:11], v[142:145], v[240:243], v[8:11]
	s_setprio 0
	s_setprio 3
	v_mfma_f32_16x16x32_bf16 v[54:57], v[146:149], v[190:193], v[54:57]
	v_mfma_f32_16x16x32_bf16 v[50:53], v[182:185], v[190:193], v[50:53]
	v_mfma_f32_16x16x32_bf16 v[38:41], v[146:149], v[220:223], v[38:41]
	v_mfma_f32_16x16x32_bf16 v[34:37], v[182:185], v[220:223], v[34:37]
	v_mfma_f32_16x16x32_bf16 v[20:23], v[146:149], v[228:231], v[20:23]
	v_mfma_f32_16x16x32_bf16 v[16:19], v[182:185], v[228:231], v[16:19]
	v_mfma_f32_16x16x32_bf16 v[4:7], v[146:149], v[236:239], v[4:7]
	v_mfma_f32_16x16x32_bf16 v[0:3], v[182:185], v[236:239], v[0:3]
	v_mfma_f32_16x16x32_bf16 v[54:57], v[150:153], v[194:197], v[54:57]
	v_mfma_f32_16x16x32_bf16 v[50:53], v[186:189], v[194:197], v[50:53]
	v_mfma_f32_16x16x32_bf16 v[38:41], v[150:153], v[224:227], v[38:41]
	v_mfma_f32_16x16x32_bf16 v[34:37], v[186:189], v[224:227], v[34:37]
	v_mfma_f32_16x16x32_bf16 v[20:23], v[150:153], v[232:235], v[20:23]
	v_mfma_f32_16x16x32_bf16 v[16:19], v[186:189], v[232:235], v[16:19]
	v_mfma_f32_16x16x32_bf16 v[4:7], v[150:153], v[240:243], v[4:7]
	v_mfma_f32_16x16x32_bf16 v[0:3], v[186:189], v[240:243], v[0:3]
	s_setprio 0
	s_barrier
	s_add_i32 s62, s62, 2
	s_add_u32 s28, s28, 0x100
	s_addc_u32 s29, s29, 0
	s_cmp_gt_u32 s62, 41
	s_mov_b64 s[58:59], s[56:57]
	s_cbranch_scc0 .LBB0_2858
	s_and_b64 vcc, exec, s[52:53]
	s_cbranch_vccz .LBB0_2861
	s_barrier

.LBB0_2949:
	s_add_u32 s2, s40, s48
	s_addc_u32 s3, s41, s49
	s_add_u32 s2, s2, 0x100
	s_addc_u32 s3, s3, 0
	s_add_u32 s50, s52, s48
	s_addc_u32 s51, s53, s49
	s_add_i32 s57, 0, 0x10000
	s_cmpk_eq_i32 s48, 0x1500
	s_cselect_b32 s3, s43, s3
	s_cselect_b32 s2, s42, s2
	v_add_u32_e32 v152, s57, v146
	s_cselect_b32 s51, s39, s51
	s_cselect_b32 s50, s38, s50
	s_add_i32 s60, 0, 0x14000
	ds_read_b128 v[148:151], v152
	ds_read_b128 v[162:165], v152 offset:1024
	ds_read_b128 v[166:169], v152 offset:2048
	ds_read_b128 v[170:173], v152 offset:3072
	v_add_u32_e32 v152, s60, v146
	ds_read_b128 v[174:177], v152
	ds_read_b128 v[178:181], v152 offset:1024
	ds_read_b128 v[182:185], v152 offset:2048
	ds_read_b128 v[186:189], v152 offset:3072
	v_lshl_add_u64 v[152:153], v[140:141], 0, s[48:49]
	s_add_i32 m0, s12, 0xc000
	ds_read_b128 v[192:195], v147
	ds_read_b128 v[196:199], v147 offset:1024
	ds_read_b128 v[200:203], v147 offset:2048
	ds_read_b128 v[204:207], v147 offset:3072
	ds_read_b128 v[208:211], v147 offset:4096
	ds_read_b128 v[220:223], v147 offset:5120
	ds_read_b128 v[224:227], v147 offset:6144
	ds_read_b128 v[228:231], v147 offset:7168
	global_load_lds_dwordx4 v[152:153], off
	v_lshl_add_u64 v[152:153], v[142:143], 0, s[48:49]
	s_add_i32 m0, s12, 0xe000
	s_nop 0
	global_load_lds_dwordx4 v[152:153], off
	s_waitcnt vmcnt(8)
	s_waitcnt lgkmcnt(0)
	s_barrier
	s_setprio 3
	s_waitcnt lgkmcnt(0)
	v_mfma_f32_16x16x32_bf16 v[126:129], v[148:151], v[192:195], v[126:129]
	v_mfma_f32_16x16x32_bf16 v[122:125], v[166:169], v[192:195], v[122:125]
	v_mfma_f32_16x16x32_bf16 v[110:113], v[148:151], v[200:203], v[110:113]
	v_mfma_f32_16x16x32_bf16 v[106:109], v[166:169], v[200:203], v[106:109]
	v_mfma_f32_16x16x32_bf16 v[94:97], v[148:151], v[208:211], v[94:97]
	v_mfma_f32_16x16x32_bf16 v[90:93], v[166:169], v[208:211], v[90:93]
	v_mfma_f32_16x16x32_bf16 v[78:81], v[148:151], v[224:227], v[78:81]
	v_mfma_f32_16x16x32_bf16 v[74:77], v[166:169], v[224:227], v[74:77]
	v_mfma_f32_16x16x32_bf16 v[126:129], v[162:165], v[196:199], v[126:129]
	v_mfma_f32_16x16x32_bf16 v[122:125], v[170:173], v[196:199], v[122:125]
	v_mfma_f32_16x16x32_bf16 v[110:113], v[162:165], v[204:207], v[110:113]
	v_mfma_f32_16x16x32_bf16 v[106:109], v[170:173], v[204:207], v[106:109]
	v_mfma_f32_16x16x32_bf16 v[94:97], v[162:165], v[220:223], v[94:97]
	v_mfma_f32_16x16x32_bf16 v[90:93], v[170:173], v[220:223], v[90:93]
	v_mfma_f32_16x16x32_bf16 v[78:81], v[162:165], v[228:231], v[78:81]
	v_mfma_f32_16x16x32_bf16 v[74:77], v[170:173], v[228:231], v[74:77]
	s_setprio 0
	s_setprio 3
	v_mfma_f32_16x16x32_bf16 v[118:121], v[174:177], v[192:195], v[118:121]
	v_mfma_f32_16x16x32_bf16 v[114:117], v[182:185], v[192:195], v[114:117]
	v_mfma_f32_16x16x32_bf16 v[102:105], v[174:177], v[200:203], v[102:105]
	v_mfma_f32_16x16x32_bf16 v[98:101], v[182:185], v[200:203], v[98:101]
	v_mfma_f32_16x16x32_bf16 v[86:89], v[174:177], v[208:211], v[86:89]
	v_mfma_f32_16x16x32_bf16 v[82:85], v[182:185], v[208:211], v[82:85]
	v_mfma_f32_16x16x32_bf16 v[70:73], v[174:177], v[224:227], v[70:73]
	v_mfma_f32_16x16x32_bf16 v[66:69], v[182:185], v[224:227], v[66:69]
	v_mfma_f32_16x16x32_bf16 v[118:121], v[178:181], v[196:199], v[118:121]
	v_mfma_f32_16x16x32_bf16 v[114:117], v[186:189], v[196:199], v[114:117]
	v_mfma_f32_16x16x32_bf16 v[102:105], v[178:181], v[204:207], v[102:105]
	v_mfma_f32_16x16x32_bf16 v[98:101], v[186:189], v[204:207], v[98:101]
	v_mfma_f32_16x16x32_bf16 v[86:89], v[178:181], v[220:223], v[86:89]
	v_mfma_f32_16x16x32_bf16 v[82:85], v[186:189], v[220:223], v[82:85]
	v_mfma_f32_16x16x32_bf16 v[70:73], v[178:181], v[228:231], v[70:73]
	v_mfma_f32_16x16x32_bf16 v[66:69], v[186:189], v[228:231], v[66:69]
	s_setprio 0
	s_barrier
	s_add_i32 s57, s57, s11
	v_lshl_add_u64 v[152:153], s[50:51], 0, v[32:33]
	s_mov_b32 m0, s57
	ds_read_b128 v[192:195], v147 offset:16384
	ds_read_b128 v[196:199], v147 offset:17408
	ds_read_b128 v[200:203], v147 offset:18432
	ds_read_b128 v[204:207], v147 offset:19456
	ds_read_b128 v[208:211], v147 offset:20480
	ds_read_b128 v[220:223], v147 offset:21504
	ds_read_b128 v[224:227], v147 offset:22528
	ds_read_b128 v[228:231], v147 offset:23552
	global_load_lds_dwordx4 v[152:153], off
	s_add_i32 m0, s57, 0x2000
	s_add_u32 s58, s50, 0xb0000
	v_lshl_add_u64 v[158:159], s[50:51], 0, v[130:131]
	s_addc_u32 s59, s51, 0
	s_add_i32 s57, s60, s11
	global_load_lds_dwordx4 v[158:159], off
	v_lshl_add_u64 v[160:161], s[58:59], 0, v[32:33]
	s_mov_b32 m0, s57
	v_lshl_add_u64 v[212:213], s[2:3], 0, v[132:133]
	global_load_lds_dwordx4 v[160:161], off
	v_lshl_add_u64 v[160:161], s[58:59], 0, v[130:131]
	s_add_i32 m0, s57, 0x2000
	s_nop 0
	global_load_lds_dwordx4 v[160:161], off
	v_lshl_add_u64 v[160:161], s[2:3], 0, v[134:135]
	s_mov_b32 m0, s12
	s_nop 0
	global_load_lds_dwordx4 v[160:161], off
	s_mov_b32 m0, s14
	s_nop 0
	global_load_lds_dwordx4 v[212:213], off
	s_waitcnt vmcnt(8)
	s_waitcnt lgkmcnt(0)
	s_barrier
	s_setprio 3
	s_waitcnt lgkmcnt(0)
	v_mfma_f32_16x16x32_bf16 v[62:65], v[148:151], v[192:195], v[62:65]
	v_mfma_f32_16x16x32_bf16 v[58:61], v[166:169], v[192:195], v[58:61]
	v_mfma_f32_16x16x32_bf16 v[46:49], v[148:151], v[200:203], v[46:49]
	v_mfma_f32_16x16x32_bf16 v[42:45], v[166:169], v[200:203], v[42:45]
	v_mfma_f32_16x16x32_bf16 v[28:31], v[148:151], v[208:211], v[28:31]
	v_mfma_f32_16x16x32_bf16 v[24:27], v[166:169], v[208:211], v[24:27]
	v_mfma_f32_16x16x32_bf16 v[12:15], v[148:151], v[224:227], v[12:15]
	v_mfma_f32_16x16x32_bf16 v[8:11], v[166:169], v[224:227], v[8:11]
	v_mfma_f32_16x16x32_bf16 v[62:65], v[162:165], v[196:199], v[62:65]
	v_mfma_f32_16x16x32_bf16 v[58:61], v[170:173], v[196:199], v[58:61]
	v_mfma_f32_16x16x32_bf16 v[46:49], v[162:165], v[204:207], v[46:49]
	v_mfma_f32_16x16x32_bf16 v[42:45], v[170:173], v[204:207], v[42:45]
	v_mfma_f32_16x16x32_bf16 v[28:31], v[162:165], v[220:223], v[28:31]
	v_mfma_f32_16x16x32_bf16 v[24:27], v[170:173], v[220:223], v[24:27]
	v_mfma_f32_16x16x32_bf16 v[12:15], v[162:165], v[228:231], v[12:15]
	v_mfma_f32_16x16x32_bf16 v[8:11], v[170:173], v[228:231], v[8:11]
	s_setprio 0
	s_setprio 3
	v_mfma_f32_16x16x32_bf16 v[54:57], v[174:177], v[192:195], v[54:57]
	v_mfma_f32_16x16x32_bf16 v[50:53], v[182:185], v[192:195], v[50:53]
	v_mfma_f32_16x16x32_bf16 v[38:41], v[174:177], v[200:203], v[38:41]
	v_mfma_f32_16x16x32_bf16 v[34:37], v[182:185], v[200:203], v[34:37]
	v_mfma_f32_16x16x32_bf16 v[20:23], v[174:177], v[208:211], v[20:23]
	v_mfma_f32_16x16x32_bf16 v[16:19], v[182:185], v[208:211], v[16:19]
	v_mfma_f32_16x16x32_bf16 v[4:7], v[174:177], v[224:227], v[4:7]
	v_mfma_f32_16x16x32_bf16 v[0:3], v[182:185], v[224:227], v[0:3]
	v_mfma_f32_16x16x32_bf16 v[54:57], v[178:181], v[196:199], v[54:57]
	v_mfma_f32_16x16x32_bf16 v[50:53], v[186:189], v[196:199], v[50:53]
	v_mfma_f32_16x16x32_bf16 v[38:41], v[178:181], v[204:207], v[38:41]
	v_mfma_f32_16x16x32_bf16 v[34:37], v[186:189], v[204:207], v[34:37]
	v_mfma_f32_16x16x32_bf16 v[20:23], v[178:181], v[220:223], v[20:23]
	v_mfma_f32_16x16x32_bf16 v[16:19], v[186:189], v[220:223], v[16:19]
	v_mfma_f32_16x16x32_bf16 v[4:7], v[178:181], v[228:231], v[4:7]
	v_mfma_f32_16x16x32_bf16 v[0:3], v[186:189], v[228:231], v[0:3]
	s_setprio 0
	s_barrier
	s_add_i32 s57, 0, 0x18000
	s_add_i32 s58, 0, 0x1c000
	v_add_u32_e32 v170, s57, v146
	v_add_u32_e32 v186, s58, v146
	ds_read_b128 v[148:151], v170
	ds_read_b128 v[162:165], v170 offset:1024
	ds_read_b128 v[166:169], v170 offset:2048
	ds_read_b128 v[170:173], v170 offset:3072
	ds_read_b128 v[174:177], v186
	ds_read_b128 v[178:181], v186 offset:1024
	ds_read_b128 v[182:185], v186 offset:2048
	ds_read_b128 v[186:189], v186 offset:3072
	s_add_u32 s2, s2, 0xb0000
	s_addc_u32 s3, s3, 0
	s_mov_b32 m0, s15
	v_lshl_add_u64 v[232:233], s[2:3], 0, v[134:135]
	ds_read_b128 v[192:195], v147 offset:32768
	ds_read_b128 v[196:199], v147 offset:33792
	ds_read_b128 v[200:203], v147 offset:34816
	ds_read_b128 v[204:207], v147 offset:35840
	ds_read_b128 v[208:211], v147 offset:36864
	ds_read_b128 v[220:223], v147 offset:37888
	ds_read_b128 v[224:227], v147 offset:38912
	ds_read_b128 v[228:231], v147 offset:39936
	global_load_lds_dwordx4 v[232:233], off
	v_lshl_add_u64 v[232:233], s[2:3], 0, v[132:133]
	s_mov_b32 m0, s17
	s_nop 0
	global_load_lds_dwordx4 v[232:233], off
	s_waitcnt vmcnt(8)
	s_waitcnt lgkmcnt(0)
	s_barrier
	s_setprio 3
	s_waitcnt lgkmcnt(0)
	v_mfma_f32_16x16x32_bf16 v[126:129], v[148:151], v[192:195], v[126:129]
	v_mfma_f32_16x16x32_bf16 v[122:125], v[166:169], v[192:195], v[122:125]
	v_mfma_f32_16x16x32_bf16 v[110:113], v[148:151], v[200:203], v[110:113]
	v_mfma_f32_16x16x32_bf16 v[106:109], v[166:169], v[200:203], v[106:109]
	v_mfma_f32_16x16x32_bf16 v[94:97], v[148:151], v[208:211], v[94:97]
	v_mfma_f32_16x16x32_bf16 v[90:93], v[166:169], v[208:211], v[90:93]
	v_mfma_f32_16x16x32_bf16 v[78:81], v[148:151], v[224:227], v[78:81]
	v_mfma_f32_16x16x32_bf16 v[74:77], v[166:169], v[224:227], v[74:77]
	v_mfma_f32_16x16x32_bf16 v[126:129], v[162:165], v[196:199], v[126:129]
	v_mfma_f32_16x16x32_bf16 v[122:125], v[170:173], v[196:199], v[122:125]
	v_mfma_f32_16x16x32_bf16 v[110:113], v[162:165], v[204:207], v[110:113]
	v_mfma_f32_16x16x32_bf16 v[106:109], v[170:173], v[204:207], v[106:109]
	v_mfma_f32_16x16x32_bf16 v[94:97], v[162:165], v[220:223], v[94:97]
	v_mfma_f32_16x16x32_bf16 v[90:93], v[170:173], v[220:223], v[90:93]
	v_mfma_f32_16x16x32_bf16 v[78:81], v[162:165], v[228:231], v[78:81]
	v_mfma_f32_16x16x32_bf16 v[74:77], v[170:173], v[228:231], v[74:77]
	s_setprio 0
	s_setprio 3
	v_mfma_f32_16x16x32_bf16 v[118:121], v[174:177], v[192:195], v[118:121]
	v_mfma_f32_16x16x32_bf16 v[114:117], v[182:185], v[192:195], v[114:117]
	v_mfma_f32_16x16x32_bf16 v[102:105], v[174:177], v[200:203], v[102:105]
	v_mfma_f32_16x16x32_bf16 v[98:101], v[182:185], v[200:203], v[98:101]
	v_mfma_f32_16x16x32_bf16 v[86:89], v[174:177], v[208:211], v[86:89]
	v_mfma_f32_16x16x32_bf16 v[82:85], v[182:185], v[208:211], v[82:85]
	v_mfma_f32_16x16x32_bf16 v[70:73], v[174:177], v[224:227], v[70:73]
	v_mfma_f32_16x16x32_bf16 v[66:69], v[182:185], v[224:227], v[66:69]
	v_mfma_f32_16x16x32_bf16 v[118:121], v[178:181], v[196:199], v[118:121]
	v_mfma_f32_16x16x32_bf16 v[114:117], v[186:189], v[196:199], v[114:117]
	v_mfma_f32_16x16x32_bf16 v[102:105], v[178:181], v[204:207], v[102:105]
	v_mfma_f32_16x16x32_bf16 v[98:101], v[186:189], v[204:207], v[98:101]
	v_mfma_f32_16x16x32_bf16 v[86:89], v[178:181], v[220:223], v[86:89]
	v_mfma_f32_16x16x32_bf16 v[82:85], v[186:189], v[220:223], v[82:85]
	v_mfma_f32_16x16x32_bf16 v[70:73], v[178:181], v[228:231], v[70:73]
	v_mfma_f32_16x16x32_bf16 v[66:69], v[186:189], v[228:231], v[66:69]
	s_setprio 0
	s_barrier
	s_add_i32 s2, s57, s11
	v_lshl_add_u64 v[152:153], v[152:153], 0, s[24:25]
	s_mov_b32 m0, s2
	ds_read_b128 v[192:195], v147 offset:49152
	ds_read_b128 v[196:199], v147 offset:50176
	ds_read_b128 v[200:203], v147 offset:51200
	ds_read_b128 v[204:207], v147 offset:52224
	ds_read_b128 v[208:211], v147 offset:53248
	ds_read_b128 v[220:223], v147 offset:54272
	ds_read_b128 v[224:227], v147 offset:55296
	ds_read_b128 v[228:231], v147 offset:56320
	global_load_lds_dwordx4 v[152:153], off
	s_add_i32 m0, s2, 0x2000
	s_add_u32 s2, s50, 0xb0080
	v_lshl_add_u64 v[152:153], v[158:159], 0, s[24:25]
	s_addc_u32 s3, s51, 0
	s_add_i32 s50, s58, s11
	global_load_lds_dwordx4 v[152:153], off
	v_lshl_add_u64 v[152:153], s[2:3], 0, v[32:33]
	s_mov_b32 m0, s50
	s_nop 0
	global_load_lds_dwordx4 v[152:153], off
	v_lshl_add_u64 v[152:153], s[2:3], 0, v[130:131]
	s_add_i32 m0, s50, 0x2000
	s_nop 0
	global_load_lds_dwordx4 v[152:153], off
	v_lshl_add_u64 v[152:153], v[160:161], 0, s[24:25]
	s_mov_b32 m0, s23
	s_nop 0
	global_load_lds_dwordx4 v[152:153], off
	v_lshl_add_u64 v[152:153], v[212:213], 0, s[24:25]
	s_mov_b32 m0, s28
	s_nop 0
	global_load_lds_dwordx4 v[152:153], off
	s_waitcnt vmcnt(8)
	s_waitcnt lgkmcnt(0)
	s_barrier
	s_setprio 3
	s_waitcnt lgkmcnt(0)
	v_mfma_f32_16x16x32_bf16 v[62:65], v[148:151], v[192:195], v[62:65]
	v_mfma_f32_16x16x32_bf16 v[58:61], v[166:169], v[192:195], v[58:61]
	v_mfma_f32_16x16x32_bf16 v[46:49], v[148:151], v[200:203], v[46:49]
	v_mfma_f32_16x16x32_bf16 v[42:45], v[166:169], v[200:203], v[42:45]
	v_mfma_f32_16x16x32_bf16 v[28:31], v[148:151], v[208:211], v[28:31]
	v_mfma_f32_16x16x32_bf16 v[24:27], v[166:169], v[208:211], v[24:27]
	v_mfma_f32_16x16x32_bf16 v[12:15], v[148:151], v[224:227], v[12:15]
	v_mfma_f32_16x16x32_bf16 v[8:11], v[166:169], v[224:227], v[8:11]
	v_mfma_f32_16x16x32_bf16 v[62:65], v[162:165], v[196:199], v[62:65]
	v_mfma_f32_16x16x32_bf16 v[58:61], v[170:173], v[196:199], v[58:61]
	v_mfma_f32_16x16x32_bf16 v[46:49], v[162:165], v[204:207], v[46:49]
	v_mfma_f32_16x16x32_bf16 v[42:45], v[170:173], v[204:207], v[42:45]
	v_mfma_f32_16x16x32_bf16 v[28:31], v[162:165], v[220:223], v[28:31]
	v_mfma_f32_16x16x32_bf16 v[24:27], v[170:173], v[220:223], v[24:27]
	v_mfma_f32_16x16x32_bf16 v[12:15], v[162:165], v[228:231], v[12:15]
	v_mfma_f32_16x16x32_bf16 v[8:11], v[170:173], v[228:231], v[8:11]
	s_setprio 0
	s_setprio 3
	v_mfma_f32_16x16x32_bf16 v[54:57], v[174:177], v[192:195], v[54:57]
	v_mfma_f32_16x16x32_bf16 v[50:53], v[182:185], v[192:195], v[50:53]
	v_mfma_f32_16x16x32_bf16 v[38:41], v[174:177], v[200:203], v[38:41]
	v_mfma_f32_16x16x32_bf16 v[34:37], v[182:185], v[200:203], v[34:37]
	v_mfma_f32_16x16x32_bf16 v[20:23], v[174:177], v[208:211], v[20:23]
	v_mfma_f32_16x16x32_bf16 v[16:19], v[182:185], v[208:211], v[16:19]
	v_mfma_f32_16x16x32_bf16 v[4:7], v[174:177], v[224:227], v[4:7]
	v_mfma_f32_16x16x32_bf16 v[0:3], v[182:185], v[224:227], v[0:3]
	v_mfma_f32_16x16x32_bf16 v[54:57], v[178:181], v[196:199], v[54:57]
	v_mfma_f32_16x16x32_bf16 v[50:53], v[186:189], v[196:199], v[50:53]
	v_mfma_f32_16x16x32_bf16 v[38:41], v[178:181], v[204:207], v[38:41]
	v_mfma_f32_16x16x32_bf16 v[34:37], v[186:189], v[204:207], v[34:37]
	v_mfma_f32_16x16x32_bf16 v[20:23], v[178:181], v[220:223], v[20:23]
	v_mfma_f32_16x16x32_bf16 v[16:19], v[186:189], v[220:223], v[16:19]
	v_mfma_f32_16x16x32_bf16 v[4:7], v[178:181], v[228:231], v[4:7]
	v_mfma_f32_16x16x32_bf16 v[0:3], v[186:189], v[228:231], v[0:3]
	s_setprio 0
	s_barrier
	s_add_i32 s56, s56, 2
	s_add_u32 s48, s48, 0x100
	s_addc_u32 s49, s49, 0
	s_cmp_gt_u32 s56, 41
	s_cbranch_scc0 .LBB0_2949
	s_add_u32 s2, s52, 0xffffff00
	s_addc_u32 s3, s53, -1
	s_and_b64 vcc, exec, s[36:37]
	s_cbranch_vccnz .LBB0_2936
	v_mov_b32_e32 v0, 0
	s_mov_b32 s30, s31
	s_mov_b32 s20, s54
	s_mov_b64 s[40:41], s[42:43]
	s_mov_b32 s29, s55
	v_mov_b32_e32 v1, v0
	v_mov_b32_e32 v2, v0
	v_mov_b32_e32 v3, v0
	v_mov_b32_e32 v4, v0
	v_mov_b32_e32 v5, v0
	v_mov_b32_e32 v6, v0
	v_mov_b32_e32 v7, v0
	v_mov_b32_e32 v16, v0
	v_mov_b32_e32 v17, v0
	v_mov_b32_e32 v18, v0
	v_mov_b32_e32 v19, v0
	v_mov_b32_e32 v20, v0
	v_mov_b32_e32 v21, v0
	v_mov_b32_e32 v22, v0
	v_mov_b32_e32 v23, v0
	v_mov_b32_e32 v34, v0
	v_mov_b32_e32 v35, v0
	v_mov_b32_e32 v36, v0
	v_mov_b32_e32 v37, v0
	v_mov_b32_e32 v38, v0
	v_mov_b32_e32 v39, v0
	v_mov_b32_e32 v40, v0
	v_mov_b32_e32 v41, v0
	v_mov_b32_e32 v50, v0
	v_mov_b32_e32 v51, v0
	v_mov_b32_e32 v52, v0
	v_mov_b32_e32 v53, v0
	v_mov_b32_e32 v54, v0
	v_mov_b32_e32 v55, v0
	v_mov_b32_e32 v56, v0
	v_mov_b32_e32 v57, v0
	v_mov_b32_e32 v8, v0
	v_mov_b32_e32 v9, v0
	v_mov_b32_e32 v10, v0
	v_mov_b32_e32 v11, v0
	v_mov_b32_e32 v12, v0
	v_mov_b32_e32 v13, v0
	v_mov_b32_e32 v14, v0
	v_mov_b32_e32 v15, v0
	v_mov_b32_e32 v24, v0
	v_mov_b32_e32 v25, v0
	v_mov_b32_e32 v26, v0
	v_mov_b32_e32 v27, v0
	v_mov_b32_e32 v28, v0
	v_mov_b32_e32 v29, v0
	v_mov_b32_e32 v30, v0
	v_mov_b32_e32 v31, v0
	v_mov_b32_e32 v42, v0
	v_mov_b32_e32 v43, v0
	v_mov_b32_e32 v44, v0
	v_mov_b32_e32 v45, v0
	v_mov_b32_e32 v46, v0
	v_mov_b32_e32 v47, v0
	v_mov_b32_e32 v48, v0
	v_mov_b32_e32 v49, v0
	v_mov_b32_e32 v58, v0
	v_mov_b32_e32 v59, v0
	v_mov_b32_e32 v60, v0
	v_mov_b32_e32 v61, v0
	v_mov_b32_e32 v62, v0
	v_mov_b32_e32 v63, v0
	v_mov_b32_e32 v64, v0
	v_mov_b32_e32 v65, v0
	v_mov_b32_e32 v66, v0
	v_mov_b32_e32 v67, v0
	v_mov_b32_e32 v68, v0
	v_mov_b32_e32 v69, v0
	v_mov_b32_e32 v70, v0
	v_mov_b32_e32 v71, v0
	v_mov_b32_e32 v72, v0
	v_mov_b32_e32 v73, v0
	v_mov_b32_e32 v82, v0
	v_mov_b32_e32 v83, v0
	v_mov_b32_e32 v84, v0
	v_mov_b32_e32 v85, v0
	v_mov_b32_e32 v86, v0
	v_mov_b32_e32 v87, v0
	v_mov_b32_e32 v88, v0
	v_mov_b32_e32 v89, v0
	v_mov_b32_e32 v98, v0
	v_mov_b32_e32 v99, v0
	v_mov_b32_e32 v100, v0
	v_mov_b32_e32 v101, v0
	v_mov_b32_e32 v102, v0
	v_mov_b32_e32 v103, v0
	v_mov_b32_e32 v104, v0
	v_mov_b32_e32 v105, v0
	v_mov_b32_e32 v114, v0
	v_mov_b32_e32 v115, v0
	v_mov_b32_e32 v116, v0
	v_mov_b32_e32 v117, v0
	v_mov_b32_e32 v118, v0
	v_mov_b32_e32 v119, v0
	v_mov_b32_e32 v120, v0
	v_mov_b32_e32 v121, v0
	v_mov_b32_e32 v74, v0
	v_mov_b32_e32 v75, v0
	v_mov_b32_e32 v76, v0
	v_mov_b32_e32 v77, v0
	v_mov_b32_e32 v78, v0
	v_mov_b32_e32 v79, v0
	v_mov_b32_e32 v80, v0
	v_mov_b32_e32 v81, v0
	v_mov_b32_e32 v90, v0
	v_mov_b32_e32 v91, v0
	v_mov_b32_e32 v92, v0
	v_mov_b32_e32 v93, v0
	v_mov_b32_e32 v94, v0
	v_mov_b32_e32 v95, v0
	v_mov_b32_e32 v96, v0
	v_mov_b32_e32 v97, v0
	v_mov_b32_e32 v106, v0
	v_mov_b32_e32 v107, v0
	v_mov_b32_e32 v108, v0
	v_mov_b32_e32 v109, v0
	v_mov_b32_e32 v110, v0
	v_mov_b32_e32 v111, v0
	v_mov_b32_e32 v112, v0
	v_mov_b32_e32 v113, v0
	v_mov_b32_e32 v122, v0
	v_mov_b32_e32 v123, v0
	v_mov_b32_e32 v124, v0
	v_mov_b32_e32 v125, v0
	v_mov_b32_e32 v126, v0
	v_mov_b32_e32 v127, v0
	v_mov_b32_e32 v128, v0
	v_mov_b32_e32 v129, v0
	s_andn2_b64 vcc, exec, s[34:35]
	s_cbranch_vccnz .LBB0_2937
